# scan steps trimmed in pass 1 (fused) and pass 2: two dot accumulators with one negate-add, v operand via d16_hi load into a zeroed register
# baseline (speedup 1.0000x reference)
; #define MKR(ptr) __builtin_amdgcn_make_buffer_rsrc((void*)(ptr), 0, 0x7fffffff, 0x00027000)
; __device__ __forceinline__ void scan_pass2(const Params& p, int d) {
;     ...
;     for (int item = blockIdx.x * 8 + wid; item < 32 * NC; item += gridDim.x * 8) {
;         const int bh = item / NC, c = item - bh * NC, b = bh >> 4, h = bh & 15;
;         const int t0 = d ? (SEQ - 1 - c * LC) : c * LC;
;         const size_t off0 = ((size_t)(b * SEQ + t0)) * RW + h * 64; const long stp = d ? -(long)RW : (long)RW;
;         const unsigned ob4 = (unsigned)(off0 * 4), ob2 = (unsigned)(off0 * 2);
;         const __amdgpu_buffer_rsrc_t rW = MKR(Wd), rA = MKR(A), rB = MKR(Bd), rK = MKR(KB), rV = MKR(V), rR = MKR(R), rY = MKR(Y);
;         const f32x4 ka4 = *(const f32x4*)(p.k_a + h * 64 + (lane & 15) * 4), c04 = 1.0f - ka4;
;         float S[64];
;         if (c == 0) {
; #pragma unroll
;             for (int i = 0; i < 64; ++i) S[i] = 0.f;
;         } else { const float* si = SIT + ((size_t)(bh * NC + c)) * 4096 + lane * 64;
; #pragma unroll
;             for (int i = 0; i < 16; ++i) { const f32x4 q = *(const f32x4*)(si + 4 * i); S[4 * i] = q[0]; S[4 * i + 1] = q[1]; S[4 * i + 2] = q[2]; S[4 * i + 3] = q[3]; } }
;     ...
;         In2 i0, i1; LD2(i0, 0);
.Lmy_p2d0_item:
	s_cmpk_gt_i32 s0, 0x7ff
	s_cbranch_scc1 .Lmy_p2d0_end
	s_lshr_b32 s86, s0, 6
	s_and_b32 s85, s0, 63
	s_and_b32 s87, s86, 15
	s_lshr_b32 s6, s86, 4
	s_lshl_b32 s6, s6, 14
	s_lshl_b32 s7, s85, 8
	s_add_u32 s6, s6, s7
	s_lshl_b32 s6, s6, 10
	s_lshl_b32 s7, s87, 6
	s_add_u32 s84, s6, s7
	s_lshl_b32 s6, s84, 2
	s_lshl_b32 s7, s84, 1
	s_mov_b32 s72, s6
	s_mov_b32 s76, s7
	s_mov_b32 s78, s6
	s_mov_b32 s79, s6
	s_lshl_b32 s8, s87, 8
	s_add_u32 s4, s42, s8
	s_addc_u32 s5, s43, 0
	global_load_dwordx4 v[188:191], v204, s[4:5]
	v_mov_b32_e32 v114, 0
	v_mov_b32_e32 v134, 0
	v_mov_b32_e32 v154, 0
	v_mov_b32_e32 v174, 0
	buffer_load_dwordx4 v[96:99], v232, s[64:67], s72 offen
	buffer_load_dwordx4 v[100:103], v233, s[64:67], s72 offen
	buffer_load_dwordx4 v[104:107], v234, s[64:67], s72 offen
	buffer_load_dwordx4 v[108:111], v235, s[64:67], s72 offen
	buffer_load_dwordx2 v[112:113], v236, s[64:67], s76 offen
	buffer_load_short_d16_hi v114, v237, s[64:67], s76 offen
	s_add_u32 s72, s72, 0x1000
	s_add_u32 s76, s76, 0x800
	buffer_load_dwordx4 v[116:119], v232, s[64:67], s72 offen
	buffer_load_dwordx4 v[120:123], v233, s[64:67], s72 offen
	buffer_load_dwordx4 v[124:127], v234, s[64:67], s72 offen
	buffer_load_dwordx4 v[128:131], v235, s[64:67], s72 offen
	buffer_load_dwordx2 v[132:133], v236, s[64:67], s76 offen
	buffer_load_short_d16_hi v134, v237, s[64:67], s76 offen
	s_add_u32 s72, s72, 0x1000
	s_add_u32 s76, s76, 0x800
	buffer_load_dwordx4 v[136:139], v232, s[64:67], s72 offen
	buffer_load_dwordx4 v[140:143], v233, s[64:67], s72 offen
	buffer_load_dwordx4 v[144:147], v234, s[64:67], s72 offen
	buffer_load_dwordx4 v[148:151], v235, s[64:67], s72 offen
	buffer_load_dwordx2 v[152:153], v236, s[64:67], s76 offen
	buffer_load_short_d16_hi v154, v237, s[64:67], s76 offen
	s_add_u32 s72, s72, 0x1000
	s_add_u32 s76, s76, 0x800
	s_cmp_eq_u32 s85, 0
	s_cbranch_scc1 .Lmy_p2d0_zero
	s_lshl_b32 s8, s0, 14
	s_add_u32 s8, s8, 0x3da00000
	s_add_u32 s4, s56, s8
	s_addc_u32 s5, s57, 0
	global_load_dwordx4 v[0:3], v210, s[4:5] offset:0
	global_load_dwordx4 v[4:7], v210, s[4:5] offset:16
	global_load_dwordx4 v[8:11], v210, s[4:5] offset:32
	global_load_dwordx4 v[12:15], v210, s[4:5] offset:48
	global_load_dwordx4 v[16:19], v210, s[4:5] offset:64
	global_load_dwordx4 v[20:23], v210, s[4:5] offset:80
	global_load_dwordx4 v[24:27], v210, s[4:5] offset:96
	global_load_dwordx4 v[28:31], v210, s[4:5] offset:112
	global_load_dwordx4 v[32:35], v210, s[4:5] offset:128
	global_load_dwordx4 v[36:39], v210, s[4:5] offset:144
	global_load_dwordx4 v[40:43], v210, s[4:5] offset:160
	global_load_dwordx4 v[44:47], v210, s[4:5] offset:176
	global_load_dwordx4 v[48:51], v210, s[4:5] offset:192
	global_load_dwordx4 v[52:55], v210, s[4:5] offset:208
	global_load_dwordx4 v[56:59], v210, s[4:5] offset:224
	global_load_dwordx4 v[60:63], v210, s[4:5] offset:240
	s_branch .Lmy_p2d0_init_done

; #define SB __builtin_amdgcn_sched_barrier(0)
; #define ST2(set, s) { DERIVE_BK(set); float sd[4]; ScanK<0>::dot(S, set.a, sd); float y0 = set.yo, y1 = 0.f; ScanK<0>::upd(S, set, -((sd[0] + sd[1]) + (sd[2] + sd[3])), __uint_as_float(set.v << 16), y0, y1); __builtin_amdgcn_raw_buffer_store_b32(__float_as_uint(y0 + y1), rY, lo4b, ob4 + (unsigned)((int)(s) * (int)stp * 4), 0); }
;     static __device__ __forceinline__ void dot(const float (&S)[64], const f32x4& a, float (&s)[4]) {
;         if constexpr (K == 0) {
;             asm volatile("v_mul_f32_dpp %0, %4, %8 row_newbcast:%16" DPPM "v_mul_f32_dpp %1, %5, %9 row_newbcast:%16" DPPM "v_mul_f32_dpp %2, %6, %10 row_newbcast:%16" DPPM "v_mul_f32_dpp %3, %7, %11 row_newbcast:%16" DPPM
;                          "v_fmac_f32_dpp %0, %4, %12 row_newbcast:%17" DPPM "v_fmac_f32_dpp %1, %5, %13 row_newbcast:%17" DPPM "v_fmac_f32_dpp %2, %6, %14 row_newbcast:%17" DPPM "v_fmac_f32_dpp %3, %7, %15 row_newbcast:%17" DPPM
;                          : "=&v"(s[0]), "=&v"(s[1]), "=&v"(s[2]), "=&v"(s[3])
;                          : "v"(a[0]), "v"(a[1]), "v"(a[2]), "v"(a[3]), "v"(S[K]), "v"(S[K + 1]), "v"(S[K + 2]), "v"(S[K + 3]), "v"(S[K + 4]), "v"(S[K + 5]), "v"(S[K + 6]), "v"(S[K + 7]), "n"(N0), "n"(N1));
;         } else
;         asm volatile("v_fmac_f32_dpp %0, %4, %8 row_newbcast:%16" DPPM "v_fmac_f32_dpp %1, %5, %9 row_newbcast:%16" DPPM "v_fmac_f32_dpp %2, %6, %10 row_newbcast:%16" DPPM "v_fmac_f32_dpp %3, %7, %11 row_newbcast:%16" DPPM
;                      "v_fmac_f32_dpp %0, %4, %12 row_newbcast:%17" DPPM "v_fmac_f32_dpp %1, %5, %13 row_newbcast:%17" DPPM "v_fmac_f32_dpp %2, %6, %14 row_newbcast:%17" DPPM "v_fmac_f32_dpp %3, %7, %15 row_newbcast:%17" DPPM
;                      : "+v"(s[0]), "+v"(s[1]), "+v"(s[2]), "+v"(s[3])
;                      : "v"(a[0]), "v"(a[1]), "v"(a[2]), "v"(a[3]), "v"(S[K]), "v"(S[K + 1]), "v"(S[K + 2]), "v"(S[K + 3]), "v"(S[K + 4]), "v"(S[K + 5]), "v"(S[K + 6]), "v"(S[K + 7]), "n"(N0), "n"(N1));
;         if constexpr (K + 8 < 64) ScanK<K + 8>::dot(S, a, s);
; __device__ __forceinline__ void scan_pass2(const Params& p, int d) {
;     ...
;         In2 i0, i1; LD2(i0, 0);
; #pragma unroll 1
;         for (int s = 0; s < LC; s += 2) { TOUCH2(i0); SB; LD2(i1, s + 1); SB; ST2(i0, s); TOUCH2(i1); SB; LD2(i0, s + 2); SB; ST2(i1, s + 1); }
.Lmy_p2d0_nost:
	buffer_load_dwordx4 v[156:159], v232, s[64:67], s72 offen
	buffer_load_dwordx4 v[160:163], v233, s[64:67], s72 offen
	buffer_load_dwordx4 v[164:167], v234, s[64:67], s72 offen
	buffer_load_dwordx4 v[168:171], v235, s[64:67], s72 offen
	buffer_load_dwordx2 v[172:173], v236, s[64:67], s76 offen
	buffer_load_short_d16_hi v174, v237, s[64:67], s76 offen
	s_add_u32 s72, s72, 0x1000
	s_add_u32 s76, s76, 0x800
	v_pk_mul_f32 v[224:225], v[100:101], v[216:217]
	v_pk_mul_f32 v[226:227], v[102:103], v[218:219]
	v_pk_mul_f32 v[216:217], v[216:217], v[96:97]
	v_pk_mul_f32 v[218:219], v[218:219], v[98:99]
	v_pk_fma_f32 v[184:185], v[104:105], v[188:189], v[192:193]
	v_pk_fma_f32 v[186:187], v[106:107], v[190:191], v[194:195]
	v_pk_mul_f32 v[176:177], v[100:101], v[104:105]
	v_pk_mul_f32 v[178:179], v[102:103], v[106:107]
	v_rcp_f32_e32 v220, v216
	v_rcp_f32_e32 v221, v217
	v_rcp_f32_e32 v222, v218
	v_rcp_f32_e32 v223, v219
	v_lshlrev_b32_e32 v180, 16, v112
	v_and_b32_e32 v181, 0xffff0000, v112
	v_lshlrev_b32_e32 v182, 16, v113
	v_and_b32_e32 v183, 0xffff0000, v113
	v_pk_mul_f32 v[180:181], v[180:181], v[184:185]
	v_pk_mul_f32 v[182:183], v[182:183], v[186:187]
	v_pk_mul_f32 v[228:229], v[108:109], v[216:217]
	v_pk_mul_f32 v[230:231], v[110:111], v[218:219]
	v_pk_mul_f32 v[176:177], v[176:177], v[220:221]
	v_pk_mul_f32 v[178:179], v[178:179], v[222:223]
	v_pk_mul_f32 v[180:181], v[180:181], v[220:221]
	v_pk_mul_f32 v[182:183], v[182:183], v[222:223]
	ds_write2_b32 v208, v176, v177 offset0:0 offset1:16
	ds_write2_b32 v208, v178, v179 offset0:32 offset1:48
	ds_write2_b32 v208, v180, v181 offset0:64 offset1:80
	ds_write2_b32 v208, v182, v183 offset0:96 offset1:112
	ds_read_b128 v[64:67], v209 offset:0
	ds_read_b128 v[68:71], v209 offset:16
	ds_read_b128 v[72:75], v209 offset:32
	ds_read_b128 v[76:79], v209 offset:48
	ds_read_b128 v[80:83], v209 offset:256
	ds_read_b128 v[84:87], v209 offset:272
	ds_read_b128 v[88:91], v209 offset:288
	ds_read_b128 v[92:95], v209 offset:304
	v_mul_f32_dpp v196, v224, v0 row_newbcast:0 row_mask:0xf bank_mask:0xf
	v_mul_f32_dpp v197, v225, v1 row_newbcast:0 row_mask:0xf bank_mask:0xf
	v_fmac_f32_dpp v196, v226, v2 row_newbcast:0 row_mask:0xf bank_mask:0xf
	v_fmac_f32_dpp v197, v227, v3 row_newbcast:0 row_mask:0xf bank_mask:0xf
	v_fmac_f32_dpp v196, v224, v4 row_newbcast:1 row_mask:0xf bank_mask:0xf
	v_fmac_f32_dpp v197, v225, v5 row_newbcast:1 row_mask:0xf bank_mask:0xf
	v_fmac_f32_dpp v196, v226, v6 row_newbcast:1 row_mask:0xf bank_mask:0xf
	v_fmac_f32_dpp v197, v227, v7 row_newbcast:1 row_mask:0xf bank_mask:0xf
	v_fmac_f32_dpp v196, v224, v8 row_newbcast:2 row_mask:0xf bank_mask:0xf
	v_fmac_f32_dpp v197, v225, v9 row_newbcast:2 row_mask:0xf bank_mask:0xf
	v_fmac_f32_dpp v196, v226, v10 row_newbcast:2 row_mask:0xf bank_mask:0xf
	v_fmac_f32_dpp v197, v227, v11 row_newbcast:2 row_mask:0xf bank_mask:0xf
	v_fmac_f32_dpp v196, v224, v12 row_newbcast:3 row_mask:0xf bank_mask:0xf
	v_fmac_f32_dpp v197, v225, v13 row_newbcast:3 row_mask:0xf bank_mask:0xf
	v_fmac_f32_dpp v196, v226, v14 row_newbcast:3 row_mask:0xf bank_mask:0xf
	v_fmac_f32_dpp v197, v227, v15 row_newbcast:3 row_mask:0xf bank_mask:0xf
	v_fmac_f32_dpp v196, v224, v16 row_newbcast:4 row_mask:0xf bank_mask:0xf
	v_fmac_f32_dpp v197, v225, v17 row_newbcast:4 row_mask:0xf bank_mask:0xf
	v_fmac_f32_dpp v196, v226, v18 row_newbcast:4 row_mask:0xf bank_mask:0xf
	v_fmac_f32_dpp v197, v227, v19 row_newbcast:4 row_mask:0xf bank_mask:0xf
	v_fmac_f32_dpp v196, v224, v20 row_newbcast:5 row_mask:0xf bank_mask:0xf
	v_fmac_f32_dpp v197, v225, v21 row_newbcast:5 row_mask:0xf bank_mask:0xf
	v_fmac_f32_dpp v196, v226, v22 row_newbcast:5 row_mask:0xf bank_mask:0xf
	v_fmac_f32_dpp v197, v227, v23 row_newbcast:5 row_mask:0xf bank_mask:0xf
	v_fmac_f32_dpp v196, v224, v24 row_newbcast:6 row_mask:0xf bank_mask:0xf
	v_fmac_f32_dpp v197, v225, v25 row_newbcast:6 row_mask:0xf bank_mask:0xf
	v_fmac_f32_dpp v196, v226, v26 row_newbcast:6 row_mask:0xf bank_mask:0xf
	v_fmac_f32_dpp v197, v227, v27 row_newbcast:6 row_mask:0xf bank_mask:0xf
	v_fmac_f32_dpp v196, v224, v28 row_newbcast:7 row_mask:0xf bank_mask:0xf
	v_fmac_f32_dpp v197, v225, v29 row_newbcast:7 row_mask:0xf bank_mask:0xf
	v_fmac_f32_dpp v196, v226, v30 row_newbcast:7 row_mask:0xf bank_mask:0xf
	v_fmac_f32_dpp v197, v227, v31 row_newbcast:7 row_mask:0xf bank_mask:0xf
	v_fmac_f32_dpp v196, v224, v32 row_newbcast:8 row_mask:0xf bank_mask:0xf
	v_fmac_f32_dpp v197, v225, v33 row_newbcast:8 row_mask:0xf bank_mask:0xf
	v_fmac_f32_dpp v196, v226, v34 row_newbcast:8 row_mask:0xf bank_mask:0xf
	v_fmac_f32_dpp v197, v227, v35 row_newbcast:8 row_mask:0xf bank_mask:0xf
	v_fmac_f32_dpp v196, v224, v36 row_newbcast:9 row_mask:0xf bank_mask:0xf
	v_fmac_f32_dpp v197, v225, v37 row_newbcast:9 row_mask:0xf bank_mask:0xf
	v_fmac_f32_dpp v196, v226, v38 row_newbcast:9 row_mask:0xf bank_mask:0xf
	v_fmac_f32_dpp v197, v227, v39 row_newbcast:9 row_mask:0xf bank_mask:0xf
	v_fmac_f32_dpp v196, v224, v40 row_newbcast:10 row_mask:0xf bank_mask:0xf
	v_fmac_f32_dpp v197, v225, v41 row_newbcast:10 row_mask:0xf bank_mask:0xf
	v_fmac_f32_dpp v196, v226, v42 row_newbcast:10 row_mask:0xf bank_mask:0xf
	v_fmac_f32_dpp v197, v227, v43 row_newbcast:10 row_mask:0xf bank_mask:0xf
	v_fmac_f32_dpp v196, v224, v44 row_newbcast:11 row_mask:0xf bank_mask:0xf
	v_fmac_f32_dpp v197, v225, v45 row_newbcast:11 row_mask:0xf bank_mask:0xf
	v_fmac_f32_dpp v196, v226, v46 row_newbcast:11 row_mask:0xf bank_mask:0xf
	v_fmac_f32_dpp v197, v227, v47 row_newbcast:11 row_mask:0xf bank_mask:0xf
	v_fmac_f32_dpp v196, v224, v48 row_newbcast:12 row_mask:0xf bank_mask:0xf
	v_fmac_f32_dpp v197, v225, v49 row_newbcast:12 row_mask:0xf bank_mask:0xf
	v_fmac_f32_dpp v196, v226, v50 row_newbcast:12 row_mask:0xf bank_mask:0xf
	v_fmac_f32_dpp v197, v227, v51 row_newbcast:12 row_mask:0xf bank_mask:0xf
	v_fmac_f32_dpp v196, v224, v52 row_newbcast:13 row_mask:0xf bank_mask:0xf
	v_fmac_f32_dpp v197, v225, v53 row_newbcast:13 row_mask:0xf bank_mask:0xf
	v_fmac_f32_dpp v196, v226, v54 row_newbcast:13 row_mask:0xf bank_mask:0xf
	v_fmac_f32_dpp v197, v227, v55 row_newbcast:13 row_mask:0xf bank_mask:0xf
	v_fmac_f32_dpp v196, v224, v56 row_newbcast:14 row_mask:0xf bank_mask:0xf
	v_fmac_f32_dpp v197, v225, v57 row_newbcast:14 row_mask:0xf bank_mask:0xf
	v_fmac_f32_dpp v196, v226, v58 row_newbcast:14 row_mask:0xf bank_mask:0xf
	v_fmac_f32_dpp v197, v227, v59 row_newbcast:14 row_mask:0xf bank_mask:0xf
	v_fmac_f32_dpp v196, v224, v60 row_newbcast:15 row_mask:0xf bank_mask:0xf
	v_fmac_f32_dpp v197, v225, v61 row_newbcast:15 row_mask:0xf bank_mask:0xf
	v_fmac_f32_dpp v196, v226, v62 row_newbcast:15 row_mask:0xf bank_mask:0xf
	v_fmac_f32_dpp v197, v227, v63 row_newbcast:15 row_mask:0xf bank_mask:0xf
	v_sub_f32_e64 v202, -v196, v197
	s_waitcnt lgkmcnt(0)
	s_nop 1
	v_mfma_f32_4x4x1_16b_f32 v[0:3], v64, v202, v[0:3]
	v_mfma_f32_4x4x1_16b_f32 v[4:7], v65, v202, v[4:7]
	v_mfma_f32_4x4x1_16b_f32 v[8:11], v66, v202, v[8:11]
	v_mfma_f32_4x4x1_16b_f32 v[12:15], v67, v202, v[12:15]
	v_mfma_f32_4x4x1_16b_f32 v[16:19], v68, v202, v[16:19]
	v_mfma_f32_4x4x1_16b_f32 v[20:23], v69, v202, v[20:23]
	v_mfma_f32_4x4x1_16b_f32 v[24:27], v70, v202, v[24:27]
	v_mfma_f32_4x4x1_16b_f32 v[28:31], v71, v202, v[28:31]
	v_mfma_f32_4x4x1_16b_f32 v[32:35], v72, v202, v[32:35]
	v_mfma_f32_4x4x1_16b_f32 v[36:39], v73, v202, v[36:39]
	v_mfma_f32_4x4x1_16b_f32 v[40:43], v74, v202, v[40:43]
	v_mfma_f32_4x4x1_16b_f32 v[44:47], v75, v202, v[44:47]
	v_mfma_f32_4x4x1_16b_f32 v[48:51], v76, v202, v[48:51]
	v_mfma_f32_4x4x1_16b_f32 v[52:55], v77, v202, v[52:55]
	v_mfma_f32_4x4x1_16b_f32 v[56:59], v78, v202, v[56:59]
	v_mfma_f32_4x4x1_16b_f32 v[60:63], v79, v202, v[60:63]
	v_mfma_f32_4x4x1_16b_f32 v[0:3], v80, v114, v[0:3]
	v_mfma_f32_4x4x1_16b_f32 v[4:7], v81, v114, v[4:7]
	v_mfma_f32_4x4x1_16b_f32 v[8:11], v82, v114, v[8:11]
	v_mfma_f32_4x4x1_16b_f32 v[12:15], v83, v114, v[12:15]
	v_mfma_f32_4x4x1_16b_f32 v[16:19], v84, v114, v[16:19]
	v_mfma_f32_4x4x1_16b_f32 v[20:23], v85, v114, v[20:23]
	v_mfma_f32_4x4x1_16b_f32 v[24:27], v86, v114, v[24:27]
	v_mfma_f32_4x4x1_16b_f32 v[28:31], v87, v114, v[28:31]
	v_mfma_f32_4x4x1_16b_f32 v[32:35], v88, v114, v[32:35]
	v_mfma_f32_4x4x1_16b_f32 v[36:39], v89, v114, v[36:39]
	v_mfma_f32_4x4x1_16b_f32 v[40:43], v90, v114, v[40:43]
	v_mfma_f32_4x4x1_16b_f32 v[44:47], v91, v114, v[44:47]
	v_mfma_f32_4x4x1_16b_f32 v[48:51], v92, v114, v[48:51]
	v_mfma_f32_4x4x1_16b_f32 v[52:55], v93, v114, v[52:55]
	v_mfma_f32_4x4x1_16b_f32 v[56:59], v94, v114, v[56:59]
	v_mfma_f32_4x4x1_16b_f32 v[60:63], v95, v114, v[60:63]
	v_mul_f32_dpp v200, v228, v0 row_newbcast:0 row_mask:0xf bank_mask:0xf
	v_mul_f32_dpp v201, v229, v1 row_newbcast:0 row_mask:0xf bank_mask:0xf
	v_fmac_f32_dpp v200, v230, v2 row_newbcast:0 row_mask:0xf bank_mask:0xf
	v_fmac_f32_dpp v201, v231, v3 row_newbcast:0 row_mask:0xf bank_mask:0xf
	v_fmac_f32_dpp v200, v228, v4 row_newbcast:1 row_mask:0xf bank_mask:0xf
	v_fmac_f32_dpp v201, v229, v5 row_newbcast:1 row_mask:0xf bank_mask:0xf
	v_fmac_f32_dpp v200, v230, v6 row_newbcast:1 row_mask:0xf bank_mask:0xf
	v_fmac_f32_dpp v201, v231, v7 row_newbcast:1 row_mask:0xf bank_mask:0xf
	v_fmac_f32_dpp v200, v228, v8 row_newbcast:2 row_mask:0xf bank_mask:0xf
	v_fmac_f32_dpp v201, v229, v9 row_newbcast:2 row_mask:0xf bank_mask:0xf
	v_fmac_f32_dpp v200, v230, v10 row_newbcast:2 row_mask:0xf bank_mask:0xf
	v_fmac_f32_dpp v201, v231, v11 row_newbcast:2 row_mask:0xf bank_mask:0xf
	v_fmac_f32_dpp v200, v228, v12 row_newbcast:3 row_mask:0xf bank_mask:0xf
	v_fmac_f32_dpp v201, v229, v13 row_newbcast:3 row_mask:0xf bank_mask:0xf
	v_fmac_f32_dpp v200, v230, v14 row_newbcast:3 row_mask:0xf bank_mask:0xf
	v_fmac_f32_dpp v201, v231, v15 row_newbcast:3 row_mask:0xf bank_mask:0xf
	v_fmac_f32_dpp v200, v228, v16 row_newbcast:4 row_mask:0xf bank_mask:0xf
	v_fmac_f32_dpp v201, v229, v17 row_newbcast:4 row_mask:0xf bank_mask:0xf
	v_fmac_f32_dpp v200, v230, v18 row_newbcast:4 row_mask:0xf bank_mask:0xf
	v_fmac_f32_dpp v201, v231, v19 row_newbcast:4 row_mask:0xf bank_mask:0xf
	v_fmac_f32_dpp v200, v228, v20 row_newbcast:5 row_mask:0xf bank_mask:0xf
	v_fmac_f32_dpp v201, v229, v21 row_newbcast:5 row_mask:0xf bank_mask:0xf
	v_fmac_f32_dpp v200, v230, v22 row_newbcast:5 row_mask:0xf bank_mask:0xf
	v_fmac_f32_dpp v201, v231, v23 row_newbcast:5 row_mask:0xf bank_mask:0xf
	v_fmac_f32_dpp v200, v228, v24 row_newbcast:6 row_mask:0xf bank_mask:0xf
	v_fmac_f32_dpp v201, v229, v25 row_newbcast:6 row_mask:0xf bank_mask:0xf
	v_fmac_f32_dpp v200, v230, v26 row_newbcast:6 row_mask:0xf bank_mask:0xf
	v_fmac_f32_dpp v201, v231, v27 row_newbcast:6 row_mask:0xf bank_mask:0xf
	v_fmac_f32_dpp v200, v228, v28 row_newbcast:7 row_mask:0xf bank_mask:0xf
	v_fmac_f32_dpp v201, v229, v29 row_newbcast:7 row_mask:0xf bank_mask:0xf
	v_fmac_f32_dpp v200, v230, v30 row_newbcast:7 row_mask:0xf bank_mask:0xf
	v_fmac_f32_dpp v201, v231, v31 row_newbcast:7 row_mask:0xf bank_mask:0xf
	v_fmac_f32_dpp v200, v228, v32 row_newbcast:8 row_mask:0xf bank_mask:0xf
	v_fmac_f32_dpp v201, v229, v33 row_newbcast:8 row_mask:0xf bank_mask:0xf
	v_fmac_f32_dpp v200, v230, v34 row_newbcast:8 row_mask:0xf bank_mask:0xf
	v_fmac_f32_dpp v201, v231, v35 row_newbcast:8 row_mask:0xf bank_mask:0xf
	v_fmac_f32_dpp v200, v228, v36 row_newbcast:9 row_mask:0xf bank_mask:0xf
	v_fmac_f32_dpp v201, v229, v37 row_newbcast:9 row_mask:0xf bank_mask:0xf
	v_fmac_f32_dpp v200, v230, v38 row_newbcast:9 row_mask:0xf bank_mask:0xf
	v_fmac_f32_dpp v201, v231, v39 row_newbcast:9 row_mask:0xf bank_mask:0xf
	v_fmac_f32_dpp v200, v228, v40 row_newbcast:10 row_mask:0xf bank_mask:0xf
	v_fmac_f32_dpp v201, v229, v41 row_newbcast:10 row_mask:0xf bank_mask:0xf
	v_fmac_f32_dpp v200, v230, v42 row_newbcast:10 row_mask:0xf bank_mask:0xf
	v_fmac_f32_dpp v201, v231, v43 row_newbcast:10 row_mask:0xf bank_mask:0xf
	v_fmac_f32_dpp v200, v228, v44 row_newbcast:11 row_mask:0xf bank_mask:0xf
	v_fmac_f32_dpp v201, v229, v45 row_newbcast:11 row_mask:0xf bank_mask:0xf
	v_fmac_f32_dpp v200, v230, v46 row_newbcast:11 row_mask:0xf bank_mask:0xf
	v_fmac_f32_dpp v201, v231, v47 row_newbcast:11 row_mask:0xf bank_mask:0xf
	v_fmac_f32_dpp v200, v228, v48 row_newbcast:12 row_mask:0xf bank_mask:0xf
	v_fmac_f32_dpp v201, v229, v49 row_newbcast:12 row_mask:0xf bank_mask:0xf
	v_fmac_f32_dpp v200, v230, v50 row_newbcast:12 row_mask:0xf bank_mask:0xf
	v_fmac_f32_dpp v201, v231, v51 row_newbcast:12 row_mask:0xf bank_mask:0xf
	v_fmac_f32_dpp v200, v228, v52 row_newbcast:13 row_mask:0xf bank_mask:0xf
	v_fmac_f32_dpp v201, v229, v53 row_newbcast:13 row_mask:0xf bank_mask:0xf
	v_fmac_f32_dpp v200, v230, v54 row_newbcast:13 row_mask:0xf bank_mask:0xf
	v_fmac_f32_dpp v201, v231, v55 row_newbcast:13 row_mask:0xf bank_mask:0xf
	v_fmac_f32_dpp v200, v228, v56 row_newbcast:14 row_mask:0xf bank_mask:0xf
	v_fmac_f32_dpp v201, v229, v57 row_newbcast:14 row_mask:0xf bank_mask:0xf
	v_fmac_f32_dpp v200, v230, v58 row_newbcast:14 row_mask:0xf bank_mask:0xf
	v_fmac_f32_dpp v201, v231, v59 row_newbcast:14 row_mask:0xf bank_mask:0xf
	v_fmac_f32_dpp v200, v228, v60 row_newbcast:15 row_mask:0xf bank_mask:0xf
	v_fmac_f32_dpp v201, v229, v61 row_newbcast:15 row_mask:0xf bank_mask:0xf
	v_fmac_f32_dpp v200, v230, v62 row_newbcast:15 row_mask:0xf bank_mask:0xf
	v_fmac_f32_dpp v201, v231, v63 row_newbcast:15 row_mask:0xf bank_mask:0xf
	v_add_f32_e32 v200, v200, v201
	s_waitcnt vmcnt(12)
	buffer_store_dword v200, v207, s[68:71], s79 offen
	s_add_u32 s79, s79, 0x1000
	buffer_load_dwordx4 v[96:99], v232, s[64:67], s72 offen
	buffer_load_dwordx4 v[100:103], v233, s[64:67], s72 offen
	buffer_load_dwordx4 v[104:107], v234, s[64:67], s72 offen
	buffer_load_dwordx4 v[108:111], v235, s[64:67], s72 offen
	buffer_load_dwordx2 v[112:113], v236, s[64:67], s76 offen
	buffer_load_short_d16_hi v114, v237, s[64:67], s76 offen
	s_add_u32 s72, s72, 0x1000
	s_add_u32 s76, s76, 0x800
	v_pk_mul_f32 v[224:225], v[120:121], v[216:217]
	v_pk_mul_f32 v[226:227], v[122:123], v[218:219]
	v_pk_mul_f32 v[216:217], v[216:217], v[116:117]
	v_pk_mul_f32 v[218:219], v[218:219], v[118:119]
	v_pk_fma_f32 v[184:185], v[124:125], v[188:189], v[192:193]
	v_pk_fma_f32 v[186:187], v[126:127], v[190:191], v[194:195]
	v_pk_mul_f32 v[176:177], v[120:121], v[124:125]
	v_pk_mul_f32 v[178:179], v[122:123], v[126:127]
	v_rcp_f32_e32 v220, v216
	v_rcp_f32_e32 v221, v217
	v_rcp_f32_e32 v222, v218
	v_rcp_f32_e32 v223, v219
	v_lshlrev_b32_e32 v180, 16, v132
	v_and_b32_e32 v181, 0xffff0000, v132
	v_lshlrev_b32_e32 v182, 16, v133
	v_and_b32_e32 v183, 0xffff0000, v133
	v_pk_mul_f32 v[180:181], v[180:181], v[184:185]
	v_pk_mul_f32 v[182:183], v[182:183], v[186:187]
	v_pk_mul_f32 v[228:229], v[128:129], v[216:217]
	v_pk_mul_f32 v[230:231], v[130:131], v[218:219]
	v_pk_mul_f32 v[176:177], v[176:177], v[220:221]
	v_pk_mul_f32 v[178:179], v[178:179], v[222:223]
	v_pk_mul_f32 v[180:181], v[180:181], v[220:221]
	v_pk_mul_f32 v[182:183], v[182:183], v[222:223]
	ds_write2_b32 v208, v176, v177 offset0:0 offset1:16
	ds_write2_b32 v208, v178, v179 offset0:32 offset1:48
	ds_write2_b32 v208, v180, v181 offset0:64 offset1:80
	ds_write2_b32 v208, v182, v183 offset0:96 offset1:112
	ds_read_b128 v[64:67], v209 offset:0
	ds_read_b128 v[68:71], v209 offset:16
	ds_read_b128 v[72:75], v209 offset:32
	ds_read_b128 v[76:79], v209 offset:48
	ds_read_b128 v[80:83], v209 offset:256
	ds_read_b128 v[84:87], v209 offset:272
	ds_read_b128 v[88:91], v209 offset:288
	ds_read_b128 v[92:95], v209 offset:304
	v_mul_f32_dpp v196, v224, v0 row_newbcast:0 row_mask:0xf bank_mask:0xf
	v_mul_f32_dpp v197, v225, v1 row_newbcast:0 row_mask:0xf bank_mask:0xf
	v_fmac_f32_dpp v196, v226, v2 row_newbcast:0 row_mask:0xf bank_mask:0xf
	v_fmac_f32_dpp v197, v227, v3 row_newbcast:0 row_mask:0xf bank_mask:0xf
	v_fmac_f32_dpp v196, v224, v4 row_newbcast:1 row_mask:0xf bank_mask:0xf
	v_fmac_f32_dpp v197, v225, v5 row_newbcast:1 row_mask:0xf bank_mask:0xf
	v_fmac_f32_dpp v196, v226, v6 row_newbcast:1 row_mask:0xf bank_mask:0xf
	v_fmac_f32_dpp v197, v227, v7 row_newbcast:1 row_mask:0xf bank_mask:0xf
	v_fmac_f32_dpp v196, v224, v8 row_newbcast:2 row_mask:0xf bank_mask:0xf
	v_fmac_f32_dpp v197, v225, v9 row_newbcast:2 row_mask:0xf bank_mask:0xf
	v_fmac_f32_dpp v196, v226, v10 row_newbcast:2 row_mask:0xf bank_mask:0xf
	v_fmac_f32_dpp v197, v227, v11 row_newbcast:2 row_mask:0xf bank_mask:0xf
	v_fmac_f32_dpp v196, v224, v12 row_newbcast:3 row_mask:0xf bank_mask:0xf
	v_fmac_f32_dpp v197, v225, v13 row_newbcast:3 row_mask:0xf bank_mask:0xf
	v_fmac_f32_dpp v196, v226, v14 row_newbcast:3 row_mask:0xf bank_mask:0xf
	v_fmac_f32_dpp v197, v227, v15 row_newbcast:3 row_mask:0xf bank_mask:0xf
	v_fmac_f32_dpp v196, v224, v16 row_newbcast:4 row_mask:0xf bank_mask:0xf
	v_fmac_f32_dpp v197, v225, v17 row_newbcast:4 row_mask:0xf bank_mask:0xf
	v_fmac_f32_dpp v196, v226, v18 row_newbcast:4 row_mask:0xf bank_mask:0xf
	v_fmac_f32_dpp v197, v227, v19 row_newbcast:4 row_mask:0xf bank_mask:0xf
	v_fmac_f32_dpp v196, v224, v20 row_newbcast:5 row_mask:0xf bank_mask:0xf
	v_fmac_f32_dpp v197, v225, v21 row_newbcast:5 row_mask:0xf bank_mask:0xf
	v_fmac_f32_dpp v196, v226, v22 row_newbcast:5 row_mask:0xf bank_mask:0xf
	v_fmac_f32_dpp v197, v227, v23 row_newbcast:5 row_mask:0xf bank_mask:0xf
	v_fmac_f32_dpp v196, v224, v24 row_newbcast:6 row_mask:0xf bank_mask:0xf
	v_fmac_f32_dpp v197, v225, v25 row_newbcast:6 row_mask:0xf bank_mask:0xf
	v_fmac_f32_dpp v196, v226, v26 row_newbcast:6 row_mask:0xf bank_mask:0xf
	v_fmac_f32_dpp v197, v227, v27 row_newbcast:6 row_mask:0xf bank_mask:0xf
	v_fmac_f32_dpp v196, v224, v28 row_newbcast:7 row_mask:0xf bank_mask:0xf
	v_fmac_f32_dpp v197, v225, v29 row_newbcast:7 row_mask:0xf bank_mask:0xf
	v_fmac_f32_dpp v196, v226, v30 row_newbcast:7 row_mask:0xf bank_mask:0xf
	v_fmac_f32_dpp v197, v227, v31 row_newbcast:7 row_mask:0xf bank_mask:0xf
	v_fmac_f32_dpp v196, v224, v32 row_newbcast:8 row_mask:0xf bank_mask:0xf
	v_fmac_f32_dpp v197, v225, v33 row_newbcast:8 row_mask:0xf bank_mask:0xf
	v_fmac_f32_dpp v196, v226, v34 row_newbcast:8 row_mask:0xf bank_mask:0xf
	v_fmac_f32_dpp v197, v227, v35 row_newbcast:8 row_mask:0xf bank_mask:0xf
	v_fmac_f32_dpp v196, v224, v36 row_newbcast:9 row_mask:0xf bank_mask:0xf
	v_fmac_f32_dpp v197, v225, v37 row_newbcast:9 row_mask:0xf bank_mask:0xf
	v_fmac_f32_dpp v196, v226, v38 row_newbcast:9 row_mask:0xf bank_mask:0xf
	v_fmac_f32_dpp v197, v227, v39 row_newbcast:9 row_mask:0xf bank_mask:0xf
	v_fmac_f32_dpp v196, v224, v40 row_newbcast:10 row_mask:0xf bank_mask:0xf
	v_fmac_f32_dpp v197, v225, v41 row_newbcast:10 row_mask:0xf bank_mask:0xf
	v_fmac_f32_dpp v196, v226, v42 row_newbcast:10 row_mask:0xf bank_mask:0xf
	v_fmac_f32_dpp v197, v227, v43 row_newbcast:10 row_mask:0xf bank_mask:0xf
	v_fmac_f32_dpp v196, v224, v44 row_newbcast:11 row_mask:0xf bank_mask:0xf
	v_fmac_f32_dpp v197, v225, v45 row_newbcast:11 row_mask:0xf bank_mask:0xf
	v_fmac_f32_dpp v196, v226, v46 row_newbcast:11 row_mask:0xf bank_mask:0xf
	v_fmac_f32_dpp v197, v227, v47 row_newbcast:11 row_mask:0xf bank_mask:0xf
	v_fmac_f32_dpp v196, v224, v48 row_newbcast:12 row_mask:0xf bank_mask:0xf
	v_fmac_f32_dpp v197, v225, v49 row_newbcast:12 row_mask:0xf bank_mask:0xf
	v_fmac_f32_dpp v196, v226, v50 row_newbcast:12 row_mask:0xf bank_mask:0xf
	v_fmac_f32_dpp v197, v227, v51 row_newbcast:12 row_mask:0xf bank_mask:0xf
	v_fmac_f32_dpp v196, v224, v52 row_newbcast:13 row_mask:0xf bank_mask:0xf
	v_fmac_f32_dpp v197, v225, v53 row_newbcast:13 row_mask:0xf bank_mask:0xf
	v_fmac_f32_dpp v196, v226, v54 row_newbcast:13 row_mask:0xf bank_mask:0xf
	v_fmac_f32_dpp v197, v227, v55 row_newbcast:13 row_mask:0xf bank_mask:0xf
	v_fmac_f32_dpp v196, v224, v56 row_newbcast:14 row_mask:0xf bank_mask:0xf
	v_fmac_f32_dpp v197, v225, v57 row_newbcast:14 row_mask:0xf bank_mask:0xf
	v_fmac_f32_dpp v196, v226, v58 row_newbcast:14 row_mask:0xf bank_mask:0xf
	v_fmac_f32_dpp v197, v227, v59 row_newbcast:14 row_mask:0xf bank_mask:0xf
	v_fmac_f32_dpp v196, v224, v60 row_newbcast:15 row_mask:0xf bank_mask:0xf
	v_fmac_f32_dpp v197, v225, v61 row_newbcast:15 row_mask:0xf bank_mask:0xf
	v_fmac_f32_dpp v196, v226, v62 row_newbcast:15 row_mask:0xf bank_mask:0xf
	v_fmac_f32_dpp v197, v227, v63 row_newbcast:15 row_mask:0xf bank_mask:0xf
	v_sub_f32_e64 v202, -v196, v197
	s_waitcnt lgkmcnt(0)
	s_nop 1
	v_mfma_f32_4x4x1_16b_f32 v[0:3], v64, v202, v[0:3]
	v_mfma_f32_4x4x1_16b_f32 v[4:7], v65, v202, v[4:7]
	v_mfma_f32_4x4x1_16b_f32 v[8:11], v66, v202, v[8:11]
	v_mfma_f32_4x4x1_16b_f32 v[12:15], v67, v202, v[12:15]
	v_mfma_f32_4x4x1_16b_f32 v[16:19], v68, v202, v[16:19]
	v_mfma_f32_4x4x1_16b_f32 v[20:23], v69, v202, v[20:23]
	v_mfma_f32_4x4x1_16b_f32 v[24:27], v70, v202, v[24:27]
	v_mfma_f32_4x4x1_16b_f32 v[28:31], v71, v202, v[28:31]
	v_mfma_f32_4x4x1_16b_f32 v[32:35], v72, v202, v[32:35]
	v_mfma_f32_4x4x1_16b_f32 v[36:39], v73, v202, v[36:39]
	v_mfma_f32_4x4x1_16b_f32 v[40:43], v74, v202, v[40:43]
	v_mfma_f32_4x4x1_16b_f32 v[44:47], v75, v202, v[44:47]
	v_mfma_f32_4x4x1_16b_f32 v[48:51], v76, v202, v[48:51]
	v_mfma_f32_4x4x1_16b_f32 v[52:55], v77, v202, v[52:55]
	v_mfma_f32_4x4x1_16b_f32 v[56:59], v78, v202, v[56:59]
	v_mfma_f32_4x4x1_16b_f32 v[60:63], v79, v202, v[60:63]
	v_mfma_f32_4x4x1_16b_f32 v[0:3], v80, v134, v[0:3]
	v_mfma_f32_4x4x1_16b_f32 v[4:7], v81, v134, v[4:7]
	v_mfma_f32_4x4x1_16b_f32 v[8:11], v82, v134, v[8:11]
	v_mfma_f32_4x4x1_16b_f32 v[12:15], v83, v134, v[12:15]
	v_mfma_f32_4x4x1_16b_f32 v[16:19], v84, v134, v[16:19]
	v_mfma_f32_4x4x1_16b_f32 v[20:23], v85, v134, v[20:23]
	v_mfma_f32_4x4x1_16b_f32 v[24:27], v86, v134, v[24:27]
	v_mfma_f32_4x4x1_16b_f32 v[28:31], v87, v134, v[28:31]
	v_mfma_f32_4x4x1_16b_f32 v[32:35], v88, v134, v[32:35]
	v_mfma_f32_4x4x1_16b_f32 v[36:39], v89, v134, v[36:39]
	v_mfma_f32_4x4x1_16b_f32 v[40:43], v90, v134, v[40:43]
	v_mfma_f32_4x4x1_16b_f32 v[44:47], v91, v134, v[44:47]
	v_mfma_f32_4x4x1_16b_f32 v[48:51], v92, v134, v[48:51]
	v_mfma_f32_4x4x1_16b_f32 v[52:55], v93, v134, v[52:55]
	v_mfma_f32_4x4x1_16b_f32 v[56:59], v94, v134, v[56:59]
	v_mfma_f32_4x4x1_16b_f32 v[60:63], v95, v134, v[60:63]
	v_mul_f32_dpp v200, v228, v0 row_newbcast:0 row_mask:0xf bank_mask:0xf
	v_mul_f32_dpp v201, v229, v1 row_newbcast:0 row_mask:0xf bank_mask:0xf
	v_fmac_f32_dpp v200, v230, v2 row_newbcast:0 row_mask:0xf bank_mask:0xf
	v_fmac_f32_dpp v201, v231, v3 row_newbcast:0 row_mask:0xf bank_mask:0xf
	v_fmac_f32_dpp v200, v228, v4 row_newbcast:1 row_mask:0xf bank_mask:0xf
	v_fmac_f32_dpp v201, v229, v5 row_newbcast:1 row_mask:0xf bank_mask:0xf
	v_fmac_f32_dpp v200, v230, v6 row_newbcast:1 row_mask:0xf bank_mask:0xf
	v_fmac_f32_dpp v201, v231, v7 row_newbcast:1 row_mask:0xf bank_mask:0xf
	v_fmac_f32_dpp v200, v228, v8 row_newbcast:2 row_mask:0xf bank_mask:0xf
	v_fmac_f32_dpp v201, v229, v9 row_newbcast:2 row_mask:0xf bank_mask:0xf
	v_fmac_f32_dpp v200, v230, v10 row_newbcast:2 row_mask:0xf bank_mask:0xf
	v_fmac_f32_dpp v201, v231, v11 row_newbcast:2 row_mask:0xf bank_mask:0xf
	v_fmac_f32_dpp v200, v228, v12 row_newbcast:3 row_mask:0xf bank_mask:0xf
	v_fmac_f32_dpp v201, v229, v13 row_newbcast:3 row_mask:0xf bank_mask:0xf
	v_fmac_f32_dpp v200, v230, v14 row_newbcast:3 row_mask:0xf bank_mask:0xf
	v_fmac_f32_dpp v201, v231, v15 row_newbcast:3 row_mask:0xf bank_mask:0xf
	v_fmac_f32_dpp v200, v228, v16 row_newbcast:4 row_mask:0xf bank_mask:0xf
	v_fmac_f32_dpp v201, v229, v17 row_newbcast:4 row_mask:0xf bank_mask:0xf
	v_fmac_f32_dpp v200, v230, v18 row_newbcast:4 row_mask:0xf bank_mask:0xf
	v_fmac_f32_dpp v201, v231, v19 row_newbcast:4 row_mask:0xf bank_mask:0xf
	v_fmac_f32_dpp v200, v228, v20 row_newbcast:5 row_mask:0xf bank_mask:0xf
	v_fmac_f32_dpp v201, v229, v21 row_newbcast:5 row_mask:0xf bank_mask:0xf
	v_fmac_f32_dpp v200, v230, v22 row_newbcast:5 row_mask:0xf bank_mask:0xf
	v_fmac_f32_dpp v201, v231, v23 row_newbcast:5 row_mask:0xf bank_mask:0xf
	v_fmac_f32_dpp v200, v228, v24 row_newbcast:6 row_mask:0xf bank_mask:0xf
	v_fmac_f32_dpp v201, v229, v25 row_newbcast:6 row_mask:0xf bank_mask:0xf
	v_fmac_f32_dpp v200, v230, v26 row_newbcast:6 row_mask:0xf bank_mask:0xf
	v_fmac_f32_dpp v201, v231, v27 row_newbcast:6 row_mask:0xf bank_mask:0xf
	v_fmac_f32_dpp v200, v228, v28 row_newbcast:7 row_mask:0xf bank_mask:0xf
	v_fmac_f32_dpp v201, v229, v29 row_newbcast:7 row_mask:0xf bank_mask:0xf
	v_fmac_f32_dpp v200, v230, v30 row_newbcast:7 row_mask:0xf bank_mask:0xf
	v_fmac_f32_dpp v201, v231, v31 row_newbcast:7 row_mask:0xf bank_mask:0xf
	v_fmac_f32_dpp v200, v228, v32 row_newbcast:8 row_mask:0xf bank_mask:0xf
	v_fmac_f32_dpp v201, v229, v33 row_newbcast:8 row_mask:0xf bank_mask:0xf
	v_fmac_f32_dpp v200, v230, v34 row_newbcast:8 row_mask:0xf bank_mask:0xf
	v_fmac_f32_dpp v201, v231, v35 row_newbcast:8 row_mask:0xf bank_mask:0xf
	v_fmac_f32_dpp v200, v228, v36 row_newbcast:9 row_mask:0xf bank_mask:0xf
	v_fmac_f32_dpp v201, v229, v37 row_newbcast:9 row_mask:0xf bank_mask:0xf
	v_fmac_f32_dpp v200, v230, v38 row_newbcast:9 row_mask:0xf bank_mask:0xf
	v_fmac_f32_dpp v201, v231, v39 row_newbcast:9 row_mask:0xf bank_mask:0xf
	v_fmac_f32_dpp v200, v228, v40 row_newbcast:10 row_mask:0xf bank_mask:0xf
	v_fmac_f32_dpp v201, v229, v41 row_newbcast:10 row_mask:0xf bank_mask:0xf
	v_fmac_f32_dpp v200, v230, v42 row_newbcast:10 row_mask:0xf bank_mask:0xf
	v_fmac_f32_dpp v201, v231, v43 row_newbcast:10 row_mask:0xf bank_mask:0xf
	v_fmac_f32_dpp v200, v228, v44 row_newbcast:11 row_mask:0xf bank_mask:0xf
	v_fmac_f32_dpp v201, v229, v45 row_newbcast:11 row_mask:0xf bank_mask:0xf
	v_fmac_f32_dpp v200, v230, v46 row_newbcast:11 row_mask:0xf bank_mask:0xf
	v_fmac_f32_dpp v201, v231, v47 row_newbcast:11 row_mask:0xf bank_mask:0xf
	v_fmac_f32_dpp v200, v228, v48 row_newbcast:12 row_mask:0xf bank_mask:0xf
	v_fmac_f32_dpp v201, v229, v49 row_newbcast:12 row_mask:0xf bank_mask:0xf
	v_fmac_f32_dpp v200, v230, v50 row_newbcast:12 row_mask:0xf bank_mask:0xf
	v_fmac_f32_dpp v201, v231, v51 row_newbcast:12 row_mask:0xf bank_mask:0xf
	v_fmac_f32_dpp v200, v228, v52 row_newbcast:13 row_mask:0xf bank_mask:0xf
	v_fmac_f32_dpp v201, v229, v53 row_newbcast:13 row_mask:0xf bank_mask:0xf
	v_fmac_f32_dpp v200, v230, v54 row_newbcast:13 row_mask:0xf bank_mask:0xf
	v_fmac_f32_dpp v201, v231, v55 row_newbcast:13 row_mask:0xf bank_mask:0xf
	v_fmac_f32_dpp v200, v228, v56 row_newbcast:14 row_mask:0xf bank_mask:0xf
	v_fmac_f32_dpp v201, v229, v57 row_newbcast:14 row_mask:0xf bank_mask:0xf
	v_fmac_f32_dpp v200, v230, v58 row_newbcast:14 row_mask:0xf bank_mask:0xf
	v_fmac_f32_dpp v201, v231, v59 row_newbcast:14 row_mask:0xf bank_mask:0xf
	v_fmac_f32_dpp v200, v228, v60 row_newbcast:15 row_mask:0xf bank_mask:0xf
	v_fmac_f32_dpp v201, v229, v61 row_newbcast:15 row_mask:0xf bank_mask:0xf
	v_fmac_f32_dpp v200, v230, v62 row_newbcast:15 row_mask:0xf bank_mask:0xf
	v_fmac_f32_dpp v201, v231, v63 row_newbcast:15 row_mask:0xf bank_mask:0xf
	v_add_f32_e32 v200, v200, v201
	s_waitcnt vmcnt(12)
	buffer_store_dword v200, v207, s[68:71], s79 offen
	s_add_u32 s79, s79, 0x1000
	buffer_load_dwordx4 v[116:119], v232, s[64:67], s72 offen
	buffer_load_dwordx4 v[120:123], v233, s[64:67], s72 offen
	buffer_load_dwordx4 v[124:127], v234, s[64:67], s72 offen
	buffer_load_dwordx4 v[128:131], v235, s[64:67], s72 offen
	buffer_load_dwordx2 v[132:133], v236, s[64:67], s76 offen
	buffer_load_short_d16_hi v134, v237, s[64:67], s76 offen
	s_add_u32 s72, s72, 0x1000
	s_add_u32 s76, s76, 0x800
	v_pk_mul_f32 v[224:225], v[140:141], v[216:217]
	v_pk_mul_f32 v[226:227], v[142:143], v[218:219]
	v_pk_mul_f32 v[216:217], v[216:217], v[136:137]
	v_pk_mul_f32 v[218:219], v[218:219], v[138:139]
	v_pk_fma_f32 v[184:185], v[144:145], v[188:189], v[192:193]
	v_pk_fma_f32 v[186:187], v[146:147], v[190:191], v[194:195]
	v_pk_mul_f32 v[176:177], v[140:141], v[144:145]
	v_pk_mul_f32 v[178:179], v[142:143], v[146:147]
	v_rcp_f32_e32 v220, v216
	v_rcp_f32_e32 v221, v217
	v_rcp_f32_e32 v222, v218
	v_rcp_f32_e32 v223, v219
	v_lshlrev_b32_e32 v180, 16, v152
	v_and_b32_e32 v181, 0xffff0000, v152
	v_lshlrev_b32_e32 v182, 16, v153
	v_and_b32_e32 v183, 0xffff0000, v153
	v_pk_mul_f32 v[180:181], v[180:181], v[184:185]
	v_pk_mul_f32 v[182:183], v[182:183], v[186:187]
	v_pk_mul_f32 v[228:229], v[148:149], v[216:217]
	v_pk_mul_f32 v[230:231], v[150:151], v[218:219]
	v_pk_mul_f32 v[176:177], v[176:177], v[220:221]
	v_pk_mul_f32 v[178:179], v[178:179], v[222:223]
	v_pk_mul_f32 v[180:181], v[180:181], v[220:221]
	v_pk_mul_f32 v[182:183], v[182:183], v[222:223]
	ds_write2_b32 v208, v176, v177 offset0:0 offset1:16
	ds_write2_b32 v208, v178, v179 offset0:32 offset1:48
	ds_write2_b32 v208, v180, v181 offset0:64 offset1:80
	ds_write2_b32 v208, v182, v183 offset0:96 offset1:112
	ds_read_b128 v[64:67], v209 offset:0
	ds_read_b128 v[68:71], v209 offset:16
	ds_read_b128 v[72:75], v209 offset:32
	ds_read_b128 v[76:79], v209 offset:48
	ds_read_b128 v[80:83], v209 offset:256
	ds_read_b128 v[84:87], v209 offset:272
	ds_read_b128 v[88:91], v209 offset:288
	ds_read_b128 v[92:95], v209 offset:304
	v_mul_f32_dpp v196, v224, v0 row_newbcast:0 row_mask:0xf bank_mask:0xf
	v_mul_f32_dpp v197, v225, v1 row_newbcast:0 row_mask:0xf bank_mask:0xf
	v_fmac_f32_dpp v196, v226, v2 row_newbcast:0 row_mask:0xf bank_mask:0xf
	v_fmac_f32_dpp v197, v227, v3 row_newbcast:0 row_mask:0xf bank_mask:0xf
	v_fmac_f32_dpp v196, v224, v4 row_newbcast:1 row_mask:0xf bank_mask:0xf
	v_fmac_f32_dpp v197, v225, v5 row_newbcast:1 row_mask:0xf bank_mask:0xf
	v_fmac_f32_dpp v196, v226, v6 row_newbcast:1 row_mask:0xf bank_mask:0xf
	v_fmac_f32_dpp v197, v227, v7 row_newbcast:1 row_mask:0xf bank_mask:0xf
	v_fmac_f32_dpp v196, v224, v8 row_newbcast:2 row_mask:0xf bank_mask:0xf
	v_fmac_f32_dpp v197, v225, v9 row_newbcast:2 row_mask:0xf bank_mask:0xf
	v_fmac_f32_dpp v196, v226, v10 row_newbcast:2 row_mask:0xf bank_mask:0xf
	v_fmac_f32_dpp v197, v227, v11 row_newbcast:2 row_mask:0xf bank_mask:0xf
	v_fmac_f32_dpp v196, v224, v12 row_newbcast:3 row_mask:0xf bank_mask:0xf
	v_fmac_f32_dpp v197, v225, v13 row_newbcast:3 row_mask:0xf bank_mask:0xf
	v_fmac_f32_dpp v196, v226, v14 row_newbcast:3 row_mask:0xf bank_mask:0xf
	v_fmac_f32_dpp v197, v227, v15 row_newbcast:3 row_mask:0xf bank_mask:0xf
	v_fmac_f32_dpp v196, v224, v16 row_newbcast:4 row_mask:0xf bank_mask:0xf
	v_fmac_f32_dpp v197, v225, v17 row_newbcast:4 row_mask:0xf bank_mask:0xf
	v_fmac_f32_dpp v196, v226, v18 row_newbcast:4 row_mask:0xf bank_mask:0xf
	v_fmac_f32_dpp v197, v227, v19 row_newbcast:4 row_mask:0xf bank_mask:0xf
	v_fmac_f32_dpp v196, v224, v20 row_newbcast:5 row_mask:0xf bank_mask:0xf
	v_fmac_f32_dpp v197, v225, v21 row_newbcast:5 row_mask:0xf bank_mask:0xf
	v_fmac_f32_dpp v196, v226, v22 row_newbcast:5 row_mask:0xf bank_mask:0xf
	v_fmac_f32_dpp v197, v227, v23 row_newbcast:5 row_mask:0xf bank_mask:0xf
	v_fmac_f32_dpp v196, v224, v24 row_newbcast:6 row_mask:0xf bank_mask:0xf
	v_fmac_f32_dpp v197, v225, v25 row_newbcast:6 row_mask:0xf bank_mask:0xf
	v_fmac_f32_dpp v196, v226, v26 row_newbcast:6 row_mask:0xf bank_mask:0xf
	v_fmac_f32_dpp v197, v227, v27 row_newbcast:6 row_mask:0xf bank_mask:0xf
	v_fmac_f32_dpp v196, v224, v28 row_newbcast:7 row_mask:0xf bank_mask:0xf
	v_fmac_f32_dpp v197, v225, v29 row_newbcast:7 row_mask:0xf bank_mask:0xf
	v_fmac_f32_dpp v196, v226, v30 row_newbcast:7 row_mask:0xf bank_mask:0xf
	v_fmac_f32_dpp v197, v227, v31 row_newbcast:7 row_mask:0xf bank_mask:0xf
	v_fmac_f32_dpp v196, v224, v32 row_newbcast:8 row_mask:0xf bank_mask:0xf
	v_fmac_f32_dpp v197, v225, v33 row_newbcast:8 row_mask:0xf bank_mask:0xf
	v_fmac_f32_dpp v196, v226, v34 row_newbcast:8 row_mask:0xf bank_mask:0xf
	v_fmac_f32_dpp v197, v227, v35 row_newbcast:8 row_mask:0xf bank_mask:0xf
	v_fmac_f32_dpp v196, v224, v36 row_newbcast:9 row_mask:0xf bank_mask:0xf
	v_fmac_f32_dpp v197, v225, v37 row_newbcast:9 row_mask:0xf bank_mask:0xf
	v_fmac_f32_dpp v196, v226, v38 row_newbcast:9 row_mask:0xf bank_mask:0xf
	v_fmac_f32_dpp v197, v227, v39 row_newbcast:9 row_mask:0xf bank_mask:0xf
	v_fmac_f32_dpp v196, v224, v40 row_newbcast:10 row_mask:0xf bank_mask:0xf
	v_fmac_f32_dpp v197, v225, v41 row_newbcast:10 row_mask:0xf bank_mask:0xf
	v_fmac_f32_dpp v196, v226, v42 row_newbcast:10 row_mask:0xf bank_mask:0xf
	v_fmac_f32_dpp v197, v227, v43 row_newbcast:10 row_mask:0xf bank_mask:0xf
	v_fmac_f32_dpp v196, v224, v44 row_newbcast:11 row_mask:0xf bank_mask:0xf
	v_fmac_f32_dpp v197, v225, v45 row_newbcast:11 row_mask:0xf bank_mask:0xf
	v_fmac_f32_dpp v196, v226, v46 row_newbcast:11 row_mask:0xf bank_mask:0xf
	v_fmac_f32_dpp v197, v227, v47 row_newbcast:11 row_mask:0xf bank_mask:0xf
	v_fmac_f32_dpp v196, v224, v48 row_newbcast:12 row_mask:0xf bank_mask:0xf
	v_fmac_f32_dpp v197, v225, v49 row_newbcast:12 row_mask:0xf bank_mask:0xf
	v_fmac_f32_dpp v196, v226, v50 row_newbcast:12 row_mask:0xf bank_mask:0xf
	v_fmac_f32_dpp v197, v227, v51 row_newbcast:12 row_mask:0xf bank_mask:0xf
	v_fmac_f32_dpp v196, v224, v52 row_newbcast:13 row_mask:0xf bank_mask:0xf
	v_fmac_f32_dpp v197, v225, v53 row_newbcast:13 row_mask:0xf bank_mask:0xf
	v_fmac_f32_dpp v196, v226, v54 row_newbcast:13 row_mask:0xf bank_mask:0xf
	v_fmac_f32_dpp v197, v227, v55 row_newbcast:13 row_mask:0xf bank_mask:0xf
	v_fmac_f32_dpp v196, v224, v56 row_newbcast:14 row_mask:0xf bank_mask:0xf
	v_fmac_f32_dpp v197, v225, v57 row_newbcast:14 row_mask:0xf bank_mask:0xf
	v_fmac_f32_dpp v196, v226, v58 row_newbcast:14 row_mask:0xf bank_mask:0xf
	v_fmac_f32_dpp v197, v227, v59 row_newbcast:14 row_mask:0xf bank_mask:0xf
	v_fmac_f32_dpp v196, v224, v60 row_newbcast:15 row_mask:0xf bank_mask:0xf
	v_fmac_f32_dpp v197, v225, v61 row_newbcast:15 row_mask:0xf bank_mask:0xf
	v_fmac_f32_dpp v196, v226, v62 row_newbcast:15 row_mask:0xf bank_mask:0xf
	v_fmac_f32_dpp v197, v227, v63 row_newbcast:15 row_mask:0xf bank_mask:0xf
	v_sub_f32_e64 v202, -v196, v197
	s_waitcnt lgkmcnt(0)
	s_nop 1
	v_mfma_f32_4x4x1_16b_f32 v[0:3], v64, v202, v[0:3]
	v_mfma_f32_4x4x1_16b_f32 v[4:7], v65, v202, v[4:7]
	v_mfma_f32_4x4x1_16b_f32 v[8:11], v66, v202, v[8:11]
	v_mfma_f32_4x4x1_16b_f32 v[12:15], v67, v202, v[12:15]
	v_mfma_f32_4x4x1_16b_f32 v[16:19], v68, v202, v[16:19]
	v_mfma_f32_4x4x1_16b_f32 v[20:23], v69, v202, v[20:23]
	v_mfma_f32_4x4x1_16b_f32 v[24:27], v70, v202, v[24:27]
	v_mfma_f32_4x4x1_16b_f32 v[28:31], v71, v202, v[28:31]
	v_mfma_f32_4x4x1_16b_f32 v[32:35], v72, v202, v[32:35]
	v_mfma_f32_4x4x1_16b_f32 v[36:39], v73, v202, v[36:39]
	v_mfma_f32_4x4x1_16b_f32 v[40:43], v74, v202, v[40:43]
	v_mfma_f32_4x4x1_16b_f32 v[44:47], v75, v202, v[44:47]
	v_mfma_f32_4x4x1_16b_f32 v[48:51], v76, v202, v[48:51]
	v_mfma_f32_4x4x1_16b_f32 v[52:55], v77, v202, v[52:55]
	v_mfma_f32_4x4x1_16b_f32 v[56:59], v78, v202, v[56:59]
	v_mfma_f32_4x4x1_16b_f32 v[60:63], v79, v202, v[60:63]
	v_mfma_f32_4x4x1_16b_f32 v[0:3], v80, v154, v[0:3]
	v_mfma_f32_4x4x1_16b_f32 v[4:7], v81, v154, v[4:7]
	v_mfma_f32_4x4x1_16b_f32 v[8:11], v82, v154, v[8:11]
	v_mfma_f32_4x4x1_16b_f32 v[12:15], v83, v154, v[12:15]
	v_mfma_f32_4x4x1_16b_f32 v[16:19], v84, v154, v[16:19]
	v_mfma_f32_4x4x1_16b_f32 v[20:23], v85, v154, v[20:23]
	v_mfma_f32_4x4x1_16b_f32 v[24:27], v86, v154, v[24:27]
	v_mfma_f32_4x4x1_16b_f32 v[28:31], v87, v154, v[28:31]
	v_mfma_f32_4x4x1_16b_f32 v[32:35], v88, v154, v[32:35]
	v_mfma_f32_4x4x1_16b_f32 v[36:39], v89, v154, v[36:39]
	v_mfma_f32_4x4x1_16b_f32 v[40:43], v90, v154, v[40:43]
	v_mfma_f32_4x4x1_16b_f32 v[44:47], v91, v154, v[44:47]
	v_mfma_f32_4x4x1_16b_f32 v[48:51], v92, v154, v[48:51]
	v_mfma_f32_4x4x1_16b_f32 v[52:55], v93, v154, v[52:55]
	v_mfma_f32_4x4x1_16b_f32 v[56:59], v94, v154, v[56:59]
	v_mfma_f32_4x4x1_16b_f32 v[60:63], v95, v154, v[60:63]
	v_mul_f32_dpp v200, v228, v0 row_newbcast:0 row_mask:0xf bank_mask:0xf
	v_mul_f32_dpp v201, v229, v1 row_newbcast:0 row_mask:0xf bank_mask:0xf
	v_fmac_f32_dpp v200, v230, v2 row_newbcast:0 row_mask:0xf bank_mask:0xf
	v_fmac_f32_dpp v201, v231, v3 row_newbcast:0 row_mask:0xf bank_mask:0xf
	v_fmac_f32_dpp v200, v228, v4 row_newbcast:1 row_mask:0xf bank_mask:0xf
	v_fmac_f32_dpp v201, v229, v5 row_newbcast:1 row_mask:0xf bank_mask:0xf
	v_fmac_f32_dpp v200, v230, v6 row_newbcast:1 row_mask:0xf bank_mask:0xf
	v_fmac_f32_dpp v201, v231, v7 row_newbcast:1 row_mask:0xf bank_mask:0xf
	v_fmac_f32_dpp v200, v228, v8 row_newbcast:2 row_mask:0xf bank_mask:0xf
	v_fmac_f32_dpp v201, v229, v9 row_newbcast:2 row_mask:0xf bank_mask:0xf
	v_fmac_f32_dpp v200, v230, v10 row_newbcast:2 row_mask:0xf bank_mask:0xf
	v_fmac_f32_dpp v201, v231, v11 row_newbcast:2 row_mask:0xf bank_mask:0xf
	v_fmac_f32_dpp v200, v228, v12 row_newbcast:3 row_mask:0xf bank_mask:0xf
	v_fmac_f32_dpp v201, v229, v13 row_newbcast:3 row_mask:0xf bank_mask:0xf
	v_fmac_f32_dpp v200, v230, v14 row_newbcast:3 row_mask:0xf bank_mask:0xf
	v_fmac_f32_dpp v201, v231, v15 row_newbcast:3 row_mask:0xf bank_mask:0xf
	v_fmac_f32_dpp v200, v228, v16 row_newbcast:4 row_mask:0xf bank_mask:0xf
	v_fmac_f32_dpp v201, v229, v17 row_newbcast:4 row_mask:0xf bank_mask:0xf
	v_fmac_f32_dpp v200, v230, v18 row_newbcast:4 row_mask:0xf bank_mask:0xf
	v_fmac_f32_dpp v201, v231, v19 row_newbcast:4 row_mask:0xf bank_mask:0xf
	v_fmac_f32_dpp v200, v228, v20 row_newbcast:5 row_mask:0xf bank_mask:0xf
	v_fmac_f32_dpp v201, v229, v21 row_newbcast:5 row_mask:0xf bank_mask:0xf
	v_fmac_f32_dpp v200, v230, v22 row_newbcast:5 row_mask:0xf bank_mask:0xf
	v_fmac_f32_dpp v201, v231, v23 row_newbcast:5 row_mask:0xf bank_mask:0xf
	v_fmac_f32_dpp v200, v228, v24 row_newbcast:6 row_mask:0xf bank_mask:0xf
	v_fmac_f32_dpp v201, v229, v25 row_newbcast:6 row_mask:0xf bank_mask:0xf
	v_fmac_f32_dpp v200, v230, v26 row_newbcast:6 row_mask:0xf bank_mask:0xf
	v_fmac_f32_dpp v201, v231, v27 row_newbcast:6 row_mask:0xf bank_mask:0xf
	v_fmac_f32_dpp v200, v228, v28 row_newbcast:7 row_mask:0xf bank_mask:0xf
	v_fmac_f32_dpp v201, v229, v29 row_newbcast:7 row_mask:0xf bank_mask:0xf
	v_fmac_f32_dpp v200, v230, v30 row_newbcast:7 row_mask:0xf bank_mask:0xf
	v_fmac_f32_dpp v201, v231, v31 row_newbcast:7 row_mask:0xf bank_mask:0xf
	v_fmac_f32_dpp v200, v228, v32 row_newbcast:8 row_mask:0xf bank_mask:0xf
	v_fmac_f32_dpp v201, v229, v33 row_newbcast:8 row_mask:0xf bank_mask:0xf
	v_fmac_f32_dpp v200, v230, v34 row_newbcast:8 row_mask:0xf bank_mask:0xf
	v_fmac_f32_dpp v201, v231, v35 row_newbcast:8 row_mask:0xf bank_mask:0xf
	v_fmac_f32_dpp v200, v228, v36 row_newbcast:9 row_mask:0xf bank_mask:0xf
	v_fmac_f32_dpp v201, v229, v37 row_newbcast:9 row_mask:0xf bank_mask:0xf
	v_fmac_f32_dpp v200, v230, v38 row_newbcast:9 row_mask:0xf bank_mask:0xf
	v_fmac_f32_dpp v201, v231, v39 row_newbcast:9 row_mask:0xf bank_mask:0xf
	v_fmac_f32_dpp v200, v228, v40 row_newbcast:10 row_mask:0xf bank_mask:0xf
	v_fmac_f32_dpp v201, v229, v41 row_newbcast:10 row_mask:0xf bank_mask:0xf
	v_fmac_f32_dpp v200, v230, v42 row_newbcast:10 row_mask:0xf bank_mask:0xf
	v_fmac_f32_dpp v201, v231, v43 row_newbcast:10 row_mask:0xf bank_mask:0xf
	v_fmac_f32_dpp v200, v228, v44 row_newbcast:11 row_mask:0xf bank_mask:0xf
	v_fmac_f32_dpp v201, v229, v45 row_newbcast:11 row_mask:0xf bank_mask:0xf
	v_fmac_f32_dpp v200, v230, v46 row_newbcast:11 row_mask:0xf bank_mask:0xf
	v_fmac_f32_dpp v201, v231, v47 row_newbcast:11 row_mask:0xf bank_mask:0xf
	v_fmac_f32_dpp v200, v228, v48 row_newbcast:12 row_mask:0xf bank_mask:0xf
	v_fmac_f32_dpp v201, v229, v49 row_newbcast:12 row_mask:0xf bank_mask:0xf
	v_fmac_f32_dpp v200, v230, v50 row_newbcast:12 row_mask:0xf bank_mask:0xf
	v_fmac_f32_dpp v201, v231, v51 row_newbcast:12 row_mask:0xf bank_mask:0xf
	v_fmac_f32_dpp v200, v228, v52 row_newbcast:13 row_mask:0xf bank_mask:0xf
	v_fmac_f32_dpp v201, v229, v53 row_newbcast:13 row_mask:0xf bank_mask:0xf
	v_fmac_f32_dpp v200, v230, v54 row_newbcast:13 row_mask:0xf bank_mask:0xf
	v_fmac_f32_dpp v201, v231, v55 row_newbcast:13 row_mask:0xf bank_mask:0xf
	v_fmac_f32_dpp v200, v228, v56 row_newbcast:14 row_mask:0xf bank_mask:0xf
	v_fmac_f32_dpp v201, v229, v57 row_newbcast:14 row_mask:0xf bank_mask:0xf
	v_fmac_f32_dpp v200, v230, v58 row_newbcast:14 row_mask:0xf bank_mask:0xf
	v_fmac_f32_dpp v201, v231, v59 row_newbcast:14 row_mask:0xf bank_mask:0xf
	v_fmac_f32_dpp v200, v228, v60 row_newbcast:15 row_mask:0xf bank_mask:0xf
	v_fmac_f32_dpp v201, v229, v61 row_newbcast:15 row_mask:0xf bank_mask:0xf
	v_fmac_f32_dpp v200, v230, v62 row_newbcast:15 row_mask:0xf bank_mask:0xf
	v_fmac_f32_dpp v201, v231, v63 row_newbcast:15 row_mask:0xf bank_mask:0xf
	v_add_f32_e32 v200, v200, v201
	s_waitcnt vmcnt(12)
	buffer_store_dword v200, v207, s[68:71], s79 offen
	s_add_u32 s79, s79, 0x1000
	buffer_load_dwordx4 v[136:139], v232, s[64:67], s72 offen
	buffer_load_dwordx4 v[140:143], v233, s[64:67], s72 offen
	buffer_load_dwordx4 v[144:147], v234, s[64:67], s72 offen
	buffer_load_dwordx4 v[148:151], v235, s[64:67], s72 offen
	buffer_load_dwordx2 v[152:153], v236, s[64:67], s76 offen
	buffer_load_short_d16_hi v154, v237, s[64:67], s76 offen
	s_add_u32 s72, s72, 0x1000
	s_add_u32 s76, s76, 0x800
	v_pk_mul_f32 v[224:225], v[160:161], v[216:217]
	v_pk_mul_f32 v[226:227], v[162:163], v[218:219]
	v_pk_mul_f32 v[216:217], v[216:217], v[156:157]
	v_pk_mul_f32 v[218:219], v[218:219], v[158:159]
	v_pk_fma_f32 v[184:185], v[164:165], v[188:189], v[192:193]
	v_pk_fma_f32 v[186:187], v[166:167], v[190:191], v[194:195]
	v_pk_mul_f32 v[176:177], v[160:161], v[164:165]
	v_pk_mul_f32 v[178:179], v[162:163], v[166:167]
	v_rcp_f32_e32 v220, v216
	v_rcp_f32_e32 v221, v217
	v_rcp_f32_e32 v222, v218
	v_rcp_f32_e32 v223, v219
	v_lshlrev_b32_e32 v180, 16, v172
	v_and_b32_e32 v181, 0xffff0000, v172
	v_lshlrev_b32_e32 v182, 16, v173
	v_and_b32_e32 v183, 0xffff0000, v173
	v_pk_mul_f32 v[180:181], v[180:181], v[184:185]
	v_pk_mul_f32 v[182:183], v[182:183], v[186:187]
	v_pk_mul_f32 v[228:229], v[168:169], v[216:217]
	v_pk_mul_f32 v[230:231], v[170:171], v[218:219]
	v_pk_mul_f32 v[176:177], v[176:177], v[220:221]
	v_pk_mul_f32 v[178:179], v[178:179], v[222:223]
	v_pk_mul_f32 v[180:181], v[180:181], v[220:221]
	v_pk_mul_f32 v[182:183], v[182:183], v[222:223]
	ds_write2_b32 v208, v176, v177 offset0:0 offset1:16
	ds_write2_b32 v208, v178, v179 offset0:32 offset1:48
	ds_write2_b32 v208, v180, v181 offset0:64 offset1:80
	ds_write2_b32 v208, v182, v183 offset0:96 offset1:112
	ds_read_b128 v[64:67], v209 offset:0
	ds_read_b128 v[68:71], v209 offset:16
	ds_read_b128 v[72:75], v209 offset:32
	ds_read_b128 v[76:79], v209 offset:48
	ds_read_b128 v[80:83], v209 offset:256
	ds_read_b128 v[84:87], v209 offset:272
	ds_read_b128 v[88:91], v209 offset:288
	ds_read_b128 v[92:95], v209 offset:304
	v_mul_f32_dpp v196, v224, v0 row_newbcast:0 row_mask:0xf bank_mask:0xf
	v_mul_f32_dpp v197, v225, v1 row_newbcast:0 row_mask:0xf bank_mask:0xf
	v_fmac_f32_dpp v196, v226, v2 row_newbcast:0 row_mask:0xf bank_mask:0xf
	v_fmac_f32_dpp v197, v227, v3 row_newbcast:0 row_mask:0xf bank_mask:0xf
	v_fmac_f32_dpp v196, v224, v4 row_newbcast:1 row_mask:0xf bank_mask:0xf
	v_fmac_f32_dpp v197, v225, v5 row_newbcast:1 row_mask:0xf bank_mask:0xf
	v_fmac_f32_dpp v196, v226, v6 row_newbcast:1 row_mask:0xf bank_mask:0xf
	v_fmac_f32_dpp v197, v227, v7 row_newbcast:1 row_mask:0xf bank_mask:0xf
	v_fmac_f32_dpp v196, v224, v8 row_newbcast:2 row_mask:0xf bank_mask:0xf
	v_fmac_f32_dpp v197, v225, v9 row_newbcast:2 row_mask:0xf bank_mask:0xf
	v_fmac_f32_dpp v196, v226, v10 row_newbcast:2 row_mask:0xf bank_mask:0xf
	v_fmac_f32_dpp v197, v227, v11 row_newbcast:2 row_mask:0xf bank_mask:0xf
	v_fmac_f32_dpp v196, v224, v12 row_newbcast:3 row_mask:0xf bank_mask:0xf
	v_fmac_f32_dpp v197, v225, v13 row_newbcast:3 row_mask:0xf bank_mask:0xf
	v_fmac_f32_dpp v196, v226, v14 row_newbcast:3 row_mask:0xf bank_mask:0xf
	v_fmac_f32_dpp v197, v227, v15 row_newbcast:3 row_mask:0xf bank_mask:0xf
	v_fmac_f32_dpp v196, v224, v16 row_newbcast:4 row_mask:0xf bank_mask:0xf
	v_fmac_f32_dpp v197, v225, v17 row_newbcast:4 row_mask:0xf bank_mask:0xf
	v_fmac_f32_dpp v196, v226, v18 row_newbcast:4 row_mask:0xf bank_mask:0xf
	v_fmac_f32_dpp v197, v227, v19 row_newbcast:4 row_mask:0xf bank_mask:0xf
	v_fmac_f32_dpp v196, v224, v20 row_newbcast:5 row_mask:0xf bank_mask:0xf
	v_fmac_f32_dpp v197, v225, v21 row_newbcast:5 row_mask:0xf bank_mask:0xf
	v_fmac_f32_dpp v196, v226, v22 row_newbcast:5 row_mask:0xf bank_mask:0xf
	v_fmac_f32_dpp v197, v227, v23 row_newbcast:5 row_mask:0xf bank_mask:0xf
	v_fmac_f32_dpp v196, v224, v24 row_newbcast:6 row_mask:0xf bank_mask:0xf
	v_fmac_f32_dpp v197, v225, v25 row_newbcast:6 row_mask:0xf bank_mask:0xf
	v_fmac_f32_dpp v196, v226, v26 row_newbcast:6 row_mask:0xf bank_mask:0xf
	v_fmac_f32_dpp v197, v227, v27 row_newbcast:6 row_mask:0xf bank_mask:0xf
	v_fmac_f32_dpp v196, v224, v28 row_newbcast:7 row_mask:0xf bank_mask:0xf
	v_fmac_f32_dpp v197, v225, v29 row_newbcast:7 row_mask:0xf bank_mask:0xf
	v_fmac_f32_dpp v196, v226, v30 row_newbcast:7 row_mask:0xf bank_mask:0xf
	v_fmac_f32_dpp v197, v227, v31 row_newbcast:7 row_mask:0xf bank_mask:0xf
	v_fmac_f32_dpp v196, v224, v32 row_newbcast:8 row_mask:0xf bank_mask:0xf
	v_fmac_f32_dpp v197, v225, v33 row_newbcast:8 row_mask:0xf bank_mask:0xf
	v_fmac_f32_dpp v196, v226, v34 row_newbcast:8 row_mask:0xf bank_mask:0xf
	v_fmac_f32_dpp v197, v227, v35 row_newbcast:8 row_mask:0xf bank_mask:0xf
	v_fmac_f32_dpp v196, v224, v36 row_newbcast:9 row_mask:0xf bank_mask:0xf
	v_fmac_f32_dpp v197, v225, v37 row_newbcast:9 row_mask:0xf bank_mask:0xf
	v_fmac_f32_dpp v196, v226, v38 row_newbcast:9 row_mask:0xf bank_mask:0xf
	v_fmac_f32_dpp v197, v227, v39 row_newbcast:9 row_mask:0xf bank_mask:0xf
	v_fmac_f32_dpp v196, v224, v40 row_newbcast:10 row_mask:0xf bank_mask:0xf
	v_fmac_f32_dpp v197, v225, v41 row_newbcast:10 row_mask:0xf bank_mask:0xf
	v_fmac_f32_dpp v196, v226, v42 row_newbcast:10 row_mask:0xf bank_mask:0xf
	v_fmac_f32_dpp v197, v227, v43 row_newbcast:10 row_mask:0xf bank_mask:0xf
	v_fmac_f32_dpp v196, v224, v44 row_newbcast:11 row_mask:0xf bank_mask:0xf
	v_fmac_f32_dpp v197, v225, v45 row_newbcast:11 row_mask:0xf bank_mask:0xf
	v_fmac_f32_dpp v196, v226, v46 row_newbcast:11 row_mask:0xf bank_mask:0xf
	v_fmac_f32_dpp v197, v227, v47 row_newbcast:11 row_mask:0xf bank_mask:0xf
	v_fmac_f32_dpp v196, v224, v48 row_newbcast:12 row_mask:0xf bank_mask:0xf
	v_fmac_f32_dpp v197, v225, v49 row_newbcast:12 row_mask:0xf bank_mask:0xf
	v_fmac_f32_dpp v196, v226, v50 row_newbcast:12 row_mask:0xf bank_mask:0xf
	v_fmac_f32_dpp v197, v227, v51 row_newbcast:12 row_mask:0xf bank_mask:0xf
	v_fmac_f32_dpp v196, v224, v52 row_newbcast:13 row_mask:0xf bank_mask:0xf
	v_fmac_f32_dpp v197, v225, v53 row_newbcast:13 row_mask:0xf bank_mask:0xf
	v_fmac_f32_dpp v196, v226, v54 row_newbcast:13 row_mask:0xf bank_mask:0xf
	v_fmac_f32_dpp v197, v227, v55 row_newbcast:13 row_mask:0xf bank_mask:0xf
	v_fmac_f32_dpp v196, v224, v56 row_newbcast:14 row_mask:0xf bank_mask:0xf
	v_fmac_f32_dpp v197, v225, v57 row_newbcast:14 row_mask:0xf bank_mask:0xf
	v_fmac_f32_dpp v196, v226, v58 row_newbcast:14 row_mask:0xf bank_mask:0xf
	v_fmac_f32_dpp v197, v227, v59 row_newbcast:14 row_mask:0xf bank_mask:0xf
	v_fmac_f32_dpp v196, v224, v60 row_newbcast:15 row_mask:0xf bank_mask:0xf
	v_fmac_f32_dpp v197, v225, v61 row_newbcast:15 row_mask:0xf bank_mask:0xf
	v_fmac_f32_dpp v196, v226, v62 row_newbcast:15 row_mask:0xf bank_mask:0xf
	v_fmac_f32_dpp v197, v227, v63 row_newbcast:15 row_mask:0xf bank_mask:0xf
	v_sub_f32_e64 v202, -v196, v197
	s_waitcnt lgkmcnt(0)
	s_nop 1
	v_mfma_f32_4x4x1_16b_f32 v[0:3], v64, v202, v[0:3]
	v_mfma_f32_4x4x1_16b_f32 v[4:7], v65, v202, v[4:7]
	v_mfma_f32_4x4x1_16b_f32 v[8:11], v66, v202, v[8:11]
	v_mfma_f32_4x4x1_16b_f32 v[12:15], v67, v202, v[12:15]
	v_mfma_f32_4x4x1_16b_f32 v[16:19], v68, v202, v[16:19]
	v_mfma_f32_4x4x1_16b_f32 v[20:23], v69, v202, v[20:23]
	v_mfma_f32_4x4x1_16b_f32 v[24:27], v70, v202, v[24:27]
	v_mfma_f32_4x4x1_16b_f32 v[28:31], v71, v202, v[28:31]
	v_mfma_f32_4x4x1_16b_f32 v[32:35], v72, v202, v[32:35]
	v_mfma_f32_4x4x1_16b_f32 v[36:39], v73, v202, v[36:39]
	v_mfma_f32_4x4x1_16b_f32 v[40:43], v74, v202, v[40:43]
	v_mfma_f32_4x4x1_16b_f32 v[44:47], v75, v202, v[44:47]
	v_mfma_f32_4x4x1_16b_f32 v[48:51], v76, v202, v[48:51]
	v_mfma_f32_4x4x1_16b_f32 v[52:55], v77, v202, v[52:55]
	v_mfma_f32_4x4x1_16b_f32 v[56:59], v78, v202, v[56:59]
	v_mfma_f32_4x4x1_16b_f32 v[60:63], v79, v202, v[60:63]
	v_mfma_f32_4x4x1_16b_f32 v[0:3], v80, v174, v[0:3]
	v_mfma_f32_4x4x1_16b_f32 v[4:7], v81, v174, v[4:7]
	v_mfma_f32_4x4x1_16b_f32 v[8:11], v82, v174, v[8:11]
	v_mfma_f32_4x4x1_16b_f32 v[12:15], v83, v174, v[12:15]
	v_mfma_f32_4x4x1_16b_f32 v[16:19], v84, v174, v[16:19]
	v_mfma_f32_4x4x1_16b_f32 v[20:23], v85, v174, v[20:23]
	v_mfma_f32_4x4x1_16b_f32 v[24:27], v86, v174, v[24:27]
	v_mfma_f32_4x4x1_16b_f32 v[28:31], v87, v174, v[28:31]
	v_mfma_f32_4x4x1_16b_f32 v[32:35], v88, v174, v[32:35]
	v_mfma_f32_4x4x1_16b_f32 v[36:39], v89, v174, v[36:39]
	v_mfma_f32_4x4x1_16b_f32 v[40:43], v90, v174, v[40:43]
	v_mfma_f32_4x4x1_16b_f32 v[44:47], v91, v174, v[44:47]
	v_mfma_f32_4x4x1_16b_f32 v[48:51], v92, v174, v[48:51]
	v_mfma_f32_4x4x1_16b_f32 v[52:55], v93, v174, v[52:55]
	v_mfma_f32_4x4x1_16b_f32 v[56:59], v94, v174, v[56:59]
	v_mfma_f32_4x4x1_16b_f32 v[60:63], v95, v174, v[60:63]
	v_mul_f32_dpp v200, v228, v0 row_newbcast:0 row_mask:0xf bank_mask:0xf
	v_mul_f32_dpp v201, v229, v1 row_newbcast:0 row_mask:0xf bank_mask:0xf
	v_fmac_f32_dpp v200, v230, v2 row_newbcast:0 row_mask:0xf bank_mask:0xf
	v_fmac_f32_dpp v201, v231, v3 row_newbcast:0 row_mask:0xf bank_mask:0xf
	v_fmac_f32_dpp v200, v228, v4 row_newbcast:1 row_mask:0xf bank_mask:0xf
	v_fmac_f32_dpp v201, v229, v5 row_newbcast:1 row_mask:0xf bank_mask:0xf
	v_fmac_f32_dpp v200, v230, v6 row_newbcast:1 row_mask:0xf bank_mask:0xf
	v_fmac_f32_dpp v201, v231, v7 row_newbcast:1 row_mask:0xf bank_mask:0xf
	v_fmac_f32_dpp v200, v228, v8 row_newbcast:2 row_mask:0xf bank_mask:0xf
	v_fmac_f32_dpp v201, v229, v9 row_newbcast:2 row_mask:0xf bank_mask:0xf
	v_fmac_f32_dpp v200, v230, v10 row_newbcast:2 row_mask:0xf bank_mask:0xf
	v_fmac_f32_dpp v201, v231, v11 row_newbcast:2 row_mask:0xf bank_mask:0xf
	v_fmac_f32_dpp v200, v228, v12 row_newbcast:3 row_mask:0xf bank_mask:0xf
	v_fmac_f32_dpp v201, v229, v13 row_newbcast:3 row_mask:0xf bank_mask:0xf
	v_fmac_f32_dpp v200, v230, v14 row_newbcast:3 row_mask:0xf bank_mask:0xf
	v_fmac_f32_dpp v201, v231, v15 row_newbcast:3 row_mask:0xf bank_mask:0xf
	v_fmac_f32_dpp v200, v228, v16 row_newbcast:4 row_mask:0xf bank_mask:0xf
	v_fmac_f32_dpp v201, v229, v17 row_newbcast:4 row_mask:0xf bank_mask:0xf
	v_fmac_f32_dpp v200, v230, v18 row_newbcast:4 row_mask:0xf bank_mask:0xf
	v_fmac_f32_dpp v201, v231, v19 row_newbcast:4 row_mask:0xf bank_mask:0xf
	v_fmac_f32_dpp v200, v228, v20 row_newbcast:5 row_mask:0xf bank_mask:0xf
	v_fmac_f32_dpp v201, v229, v21 row_newbcast:5 row_mask:0xf bank_mask:0xf
	v_fmac_f32_dpp v200, v230, v22 row_newbcast:5 row_mask:0xf bank_mask:0xf
	v_fmac_f32_dpp v201, v231, v23 row_newbcast:5 row_mask:0xf bank_mask:0xf
	v_fmac_f32_dpp v200, v228, v24 row_newbcast:6 row_mask:0xf bank_mask:0xf
	v_fmac_f32_dpp v201, v229, v25 row_newbcast:6 row_mask:0xf bank_mask:0xf
	v_fmac_f32_dpp v200, v230, v26 row_newbcast:6 row_mask:0xf bank_mask:0xf
	v_fmac_f32_dpp v201, v231, v27 row_newbcast:6 row_mask:0xf bank_mask:0xf
	v_fmac_f32_dpp v200, v228, v28 row_newbcast:7 row_mask:0xf bank_mask:0xf
	v_fmac_f32_dpp v201, v229, v29 row_newbcast:7 row_mask:0xf bank_mask:0xf
	v_fmac_f32_dpp v200, v230, v30 row_newbcast:7 row_mask:0xf bank_mask:0xf
	v_fmac_f32_dpp v201, v231, v31 row_newbcast:7 row_mask:0xf bank_mask:0xf
	v_fmac_f32_dpp v200, v228, v32 row_newbcast:8 row_mask:0xf bank_mask:0xf
	v_fmac_f32_dpp v201, v229, v33 row_newbcast:8 row_mask:0xf bank_mask:0xf
	v_fmac_f32_dpp v200, v230, v34 row_newbcast:8 row_mask:0xf bank_mask:0xf
	v_fmac_f32_dpp v201, v231, v35 row_newbcast:8 row_mask:0xf bank_mask:0xf
	v_fmac_f32_dpp v200, v228, v36 row_newbcast:9 row_mask:0xf bank_mask:0xf
	v_fmac_f32_dpp v201, v229, v37 row_newbcast:9 row_mask:0xf bank_mask:0xf
	v_fmac_f32_dpp v200, v230, v38 row_newbcast:9 row_mask:0xf bank_mask:0xf
	v_fmac_f32_dpp v201, v231, v39 row_newbcast:9 row_mask:0xf bank_mask:0xf
	v_fmac_f32_dpp v200, v228, v40 row_newbcast:10 row_mask:0xf bank_mask:0xf
	v_fmac_f32_dpp v201, v229, v41 row_newbcast:10 row_mask:0xf bank_mask:0xf
	v_fmac_f32_dpp v200, v230, v42 row_newbcast:10 row_mask:0xf bank_mask:0xf
	v_fmac_f32_dpp v201, v231, v43 row_newbcast:10 row_mask:0xf bank_mask:0xf
	v_fmac_f32_dpp v200, v228, v44 row_newbcast:11 row_mask:0xf bank_mask:0xf
	v_fmac_f32_dpp v201, v229, v45 row_newbcast:11 row_mask:0xf bank_mask:0xf
	v_fmac_f32_dpp v200, v230, v46 row_newbcast:11 row_mask:0xf bank_mask:0xf
	v_fmac_f32_dpp v201, v231, v47 row_newbcast:11 row_mask:0xf bank_mask:0xf
	v_fmac_f32_dpp v200, v228, v48 row_newbcast:12 row_mask:0xf bank_mask:0xf
	v_fmac_f32_dpp v201, v229, v49 row_newbcast:12 row_mask:0xf bank_mask:0xf
	v_fmac_f32_dpp v200, v230, v50 row_newbcast:12 row_mask:0xf bank_mask:0xf
	v_fmac_f32_dpp v201, v231, v51 row_newbcast:12 row_mask:0xf bank_mask:0xf
	v_fmac_f32_dpp v200, v228, v52 row_newbcast:13 row_mask:0xf bank_mask:0xf
	v_fmac_f32_dpp v201, v229, v53 row_newbcast:13 row_mask:0xf bank_mask:0xf
	v_fmac_f32_dpp v200, v230, v54 row_newbcast:13 row_mask:0xf bank_mask:0xf
	v_fmac_f32_dpp v201, v231, v55 row_newbcast:13 row_mask:0xf bank_mask:0xf
	v_fmac_f32_dpp v200, v228, v56 row_newbcast:14 row_mask:0xf bank_mask:0xf
	v_fmac_f32_dpp v201, v229, v57 row_newbcast:14 row_mask:0xf bank_mask:0xf
	v_fmac_f32_dpp v200, v230, v58 row_newbcast:14 row_mask:0xf bank_mask:0xf
	v_fmac_f32_dpp v201, v231, v59 row_newbcast:14 row_mask:0xf bank_mask:0xf
	v_fmac_f32_dpp v200, v228, v60 row_newbcast:15 row_mask:0xf bank_mask:0xf
	v_fmac_f32_dpp v201, v229, v61 row_newbcast:15 row_mask:0xf bank_mask:0xf
	v_fmac_f32_dpp v200, v230, v62 row_newbcast:15 row_mask:0xf bank_mask:0xf
	v_fmac_f32_dpp v201, v231, v63 row_newbcast:15 row_mask:0xf bank_mask:0xf
	v_add_f32_e32 v200, v200, v201
	s_sub_u32 s83, s83, 1
	s_cmp_eq_u32 s83, 0
	s_cbranch_scc1 .Lmy_p2d0_ldone
	s_and_b32 s9, s83, 7
	s_cmp_eq_u32 s9, 0
	s_cbranch_scc1 .Lmy_p2d0_renorm
	s_branch .Lmy_p2d0_loop

.Lmy_p2d1_item:
	s_cmpk_gt_i32 s0, 0x7ff
	s_cbranch_scc1 .Lmy_p2d1_end
	s_lshr_b32 s86, s0, 6
	s_and_b32 s85, s0, 63
	s_and_b32 s87, s86, 15
	s_lshr_b32 s6, s86, 4
	s_lshl_b32 s6, s6, 14
	s_lshl_b32 s7, s85, 8
	s_sub_u32 s7, 0x3fff, s7
	s_add_u32 s6, s6, s7
	s_lshl_b32 s6, s6, 10
	s_lshl_b32 s7, s87, 6
	s_add_u32 s84, s6, s7
	s_lshl_b32 s6, s84, 2
	s_lshl_b32 s7, s84, 1
	s_mov_b32 s72, s6
	s_mov_b32 s76, s7
	s_mov_b32 s78, s6
	s_mov_b32 s79, s6
	s_lshl_b32 s8, s87, 8
	s_add_u32 s4, s42, s8
	s_addc_u32 s5, s43, 0
	global_load_dwordx4 v[188:191], v204, s[4:5]
	v_mov_b32_e32 v114, 0
	v_mov_b32_e32 v134, 0
	v_mov_b32_e32 v154, 0
	v_mov_b32_e32 v174, 0
	buffer_load_dwordx4 v[96:99], v232, s[64:67], s72 offen
	buffer_load_dwordx4 v[100:103], v233, s[64:67], s72 offen
	buffer_load_dwordx4 v[104:107], v234, s[64:67], s72 offen
	buffer_load_dwordx4 v[108:111], v235, s[64:67], s72 offen
	buffer_load_dwordx2 v[112:113], v236, s[64:67], s76 offen
	buffer_load_short_d16_hi v114, v237, s[64:67], s76 offen
	buffer_load_dword v115, v207, s[68:71], s78 offen
	s_add_i32 s72, s72, 0xfffff000
	s_max_i32 s72, s72, 0
	s_add_i32 s76, s76, 0xfffff800
	s_max_i32 s76, s76, 0
	s_add_i32 s78, s78, 0xfffff000
	s_max_i32 s78, s78, 0
	buffer_load_dwordx4 v[116:119], v232, s[64:67], s72 offen
	buffer_load_dwordx4 v[120:123], v233, s[64:67], s72 offen
	buffer_load_dwordx4 v[124:127], v234, s[64:67], s72 offen
	buffer_load_dwordx4 v[128:131], v235, s[64:67], s72 offen
	buffer_load_dwordx2 v[132:133], v236, s[64:67], s76 offen
	buffer_load_short_d16_hi v134, v237, s[64:67], s76 offen
	buffer_load_dword v135, v207, s[68:71], s78 offen
	s_add_i32 s72, s72, 0xfffff000
	s_max_i32 s72, s72, 0
	s_add_i32 s76, s76, 0xfffff800
	s_max_i32 s76, s76, 0
	s_add_i32 s78, s78, 0xfffff000
	s_max_i32 s78, s78, 0
	buffer_load_dwordx4 v[136:139], v232, s[64:67], s72 offen
	buffer_load_dwordx4 v[140:143], v233, s[64:67], s72 offen
	buffer_load_dwordx4 v[144:147], v234, s[64:67], s72 offen
	buffer_load_dwordx4 v[148:151], v235, s[64:67], s72 offen
	buffer_load_dwordx2 v[152:153], v236, s[64:67], s76 offen
	buffer_load_short_d16_hi v154, v237, s[64:67], s76 offen
	buffer_load_dword v155, v207, s[68:71], s78 offen
	s_add_i32 s72, s72, 0xfffff000
	s_max_i32 s72, s72, 0
	s_add_i32 s76, s76, 0xfffff800
	s_max_i32 s76, s76, 0
	s_add_i32 s78, s78, 0xfffff000
	s_max_i32 s78, s78, 0
	s_cmp_eq_u32 s85, 0
	s_cbranch_scc1 .Lmy_p2d1_zero
	s_lshl_b32 s8, s0, 14
	s_add_u32 s8, s8, 0x3da00000
	s_add_u32 s4, s56, s8
	s_addc_u32 s5, s57, 0
	global_load_dwordx4 v[0:3], v210, s[4:5] offset:0
	global_load_dwordx4 v[4:7], v210, s[4:5] offset:16
	global_load_dwordx4 v[8:11], v210, s[4:5] offset:32
	global_load_dwordx4 v[12:15], v210, s[4:5] offset:48
	global_load_dwordx4 v[16:19], v210, s[4:5] offset:64
	global_load_dwordx4 v[20:23], v210, s[4:5] offset:80
	global_load_dwordx4 v[24:27], v210, s[4:5] offset:96
	global_load_dwordx4 v[28:31], v210, s[4:5] offset:112
	global_load_dwordx4 v[32:35], v210, s[4:5] offset:128
	global_load_dwordx4 v[36:39], v210, s[4:5] offset:144
	global_load_dwordx4 v[40:43], v210, s[4:5] offset:160
	global_load_dwordx4 v[44:47], v210, s[4:5] offset:176
	global_load_dwordx4 v[48:51], v210, s[4:5] offset:192
	global_load_dwordx4 v[52:55], v210, s[4:5] offset:208
	global_load_dwordx4 v[56:59], v210, s[4:5] offset:224
	global_load_dwordx4 v[60:63], v210, s[4:5] offset:240
	s_branch .Lmy_p2d1_init_done

.Lmy_p2d1_nost:
	buffer_load_dwordx4 v[156:159], v232, s[64:67], s72 offen
	buffer_load_dwordx4 v[160:163], v233, s[64:67], s72 offen
	buffer_load_dwordx4 v[164:167], v234, s[64:67], s72 offen
	buffer_load_dwordx4 v[168:171], v235, s[64:67], s72 offen
	buffer_load_dwordx2 v[172:173], v236, s[64:67], s76 offen
	buffer_load_short_d16_hi v174, v237, s[64:67], s76 offen
	buffer_load_dword v175, v207, s[68:71], s78 offen
	s_add_i32 s72, s72, 0xfffff000
	s_max_i32 s72, s72, 0
	s_add_i32 s76, s76, 0xfffff800
	s_max_i32 s76, s76, 0
	s_add_i32 s78, s78, 0xfffff000
	s_max_i32 s78, s78, 0
	v_pk_mul_f32 v[224:225], v[100:101], v[216:217]
	v_pk_mul_f32 v[226:227], v[102:103], v[218:219]
	v_pk_mul_f32 v[216:217], v[216:217], v[96:97]
	v_pk_mul_f32 v[218:219], v[218:219], v[98:99]
	v_pk_fma_f32 v[184:185], v[104:105], v[188:189], v[192:193]
	v_pk_fma_f32 v[186:187], v[106:107], v[190:191], v[194:195]
	v_pk_mul_f32 v[176:177], v[100:101], v[104:105]
	v_pk_mul_f32 v[178:179], v[102:103], v[106:107]
	v_rcp_f32_e32 v220, v216
	v_rcp_f32_e32 v221, v217
	v_rcp_f32_e32 v222, v218
	v_rcp_f32_e32 v223, v219
	v_lshlrev_b32_e32 v180, 16, v112
	v_and_b32_e32 v181, 0xffff0000, v112
	v_lshlrev_b32_e32 v182, 16, v113
	v_and_b32_e32 v183, 0xffff0000, v113
	v_pk_mul_f32 v[180:181], v[180:181], v[184:185]
	v_pk_mul_f32 v[182:183], v[182:183], v[186:187]
	v_pk_mul_f32 v[228:229], v[108:109], v[216:217]
	v_pk_mul_f32 v[230:231], v[110:111], v[218:219]
	v_pk_mul_f32 v[176:177], v[176:177], v[220:221]
	v_pk_mul_f32 v[178:179], v[178:179], v[222:223]
	v_pk_mul_f32 v[180:181], v[180:181], v[220:221]
	v_pk_mul_f32 v[182:183], v[182:183], v[222:223]
	ds_write2_b32 v208, v176, v177 offset0:0 offset1:16
	ds_write2_b32 v208, v178, v179 offset0:32 offset1:48
	ds_write2_b32 v208, v180, v181 offset0:64 offset1:80
	ds_write2_b32 v208, v182, v183 offset0:96 offset1:112
	ds_read_b128 v[64:67], v209 offset:0
	ds_read_b128 v[68:71], v209 offset:16
	ds_read_b128 v[72:75], v209 offset:32
	ds_read_b128 v[76:79], v209 offset:48
	ds_read_b128 v[80:83], v209 offset:256
	ds_read_b128 v[84:87], v209 offset:272
	ds_read_b128 v[88:91], v209 offset:288
	ds_read_b128 v[92:95], v209 offset:304
	v_mul_f32_dpp v196, v224, v0 row_newbcast:0 row_mask:0xf bank_mask:0xf
	v_mul_f32_dpp v197, v225, v1 row_newbcast:0 row_mask:0xf bank_mask:0xf
	v_fmac_f32_dpp v196, v226, v2 row_newbcast:0 row_mask:0xf bank_mask:0xf
	v_fmac_f32_dpp v197, v227, v3 row_newbcast:0 row_mask:0xf bank_mask:0xf
	v_fmac_f32_dpp v196, v224, v4 row_newbcast:1 row_mask:0xf bank_mask:0xf
	v_fmac_f32_dpp v197, v225, v5 row_newbcast:1 row_mask:0xf bank_mask:0xf
	v_fmac_f32_dpp v196, v226, v6 row_newbcast:1 row_mask:0xf bank_mask:0xf
	v_fmac_f32_dpp v197, v227, v7 row_newbcast:1 row_mask:0xf bank_mask:0xf
	v_fmac_f32_dpp v196, v224, v8 row_newbcast:2 row_mask:0xf bank_mask:0xf
	v_fmac_f32_dpp v197, v225, v9 row_newbcast:2 row_mask:0xf bank_mask:0xf
	v_fmac_f32_dpp v196, v226, v10 row_newbcast:2 row_mask:0xf bank_mask:0xf
	v_fmac_f32_dpp v197, v227, v11 row_newbcast:2 row_mask:0xf bank_mask:0xf
	v_fmac_f32_dpp v196, v224, v12 row_newbcast:3 row_mask:0xf bank_mask:0xf
	v_fmac_f32_dpp v197, v225, v13 row_newbcast:3 row_mask:0xf bank_mask:0xf
	v_fmac_f32_dpp v196, v226, v14 row_newbcast:3 row_mask:0xf bank_mask:0xf
	v_fmac_f32_dpp v197, v227, v15 row_newbcast:3 row_mask:0xf bank_mask:0xf
	v_fmac_f32_dpp v196, v224, v16 row_newbcast:4 row_mask:0xf bank_mask:0xf
	v_fmac_f32_dpp v197, v225, v17 row_newbcast:4 row_mask:0xf bank_mask:0xf
	v_fmac_f32_dpp v196, v226, v18 row_newbcast:4 row_mask:0xf bank_mask:0xf
	v_fmac_f32_dpp v197, v227, v19 row_newbcast:4 row_mask:0xf bank_mask:0xf
	v_fmac_f32_dpp v196, v224, v20 row_newbcast:5 row_mask:0xf bank_mask:0xf
	v_fmac_f32_dpp v197, v225, v21 row_newbcast:5 row_mask:0xf bank_mask:0xf
	v_fmac_f32_dpp v196, v226, v22 row_newbcast:5 row_mask:0xf bank_mask:0xf
	v_fmac_f32_dpp v197, v227, v23 row_newbcast:5 row_mask:0xf bank_mask:0xf
	v_fmac_f32_dpp v196, v224, v24 row_newbcast:6 row_mask:0xf bank_mask:0xf
	v_fmac_f32_dpp v197, v225, v25 row_newbcast:6 row_mask:0xf bank_mask:0xf
	v_fmac_f32_dpp v196, v226, v26 row_newbcast:6 row_mask:0xf bank_mask:0xf
	v_fmac_f32_dpp v197, v227, v27 row_newbcast:6 row_mask:0xf bank_mask:0xf
	v_fmac_f32_dpp v196, v224, v28 row_newbcast:7 row_mask:0xf bank_mask:0xf
	v_fmac_f32_dpp v197, v225, v29 row_newbcast:7 row_mask:0xf bank_mask:0xf
	v_fmac_f32_dpp v196, v226, v30 row_newbcast:7 row_mask:0xf bank_mask:0xf
	v_fmac_f32_dpp v197, v227, v31 row_newbcast:7 row_mask:0xf bank_mask:0xf
	v_fmac_f32_dpp v196, v224, v32 row_newbcast:8 row_mask:0xf bank_mask:0xf
	v_fmac_f32_dpp v197, v225, v33 row_newbcast:8 row_mask:0xf bank_mask:0xf
	v_fmac_f32_dpp v196, v226, v34 row_newbcast:8 row_mask:0xf bank_mask:0xf
	v_fmac_f32_dpp v197, v227, v35 row_newbcast:8 row_mask:0xf bank_mask:0xf
	v_fmac_f32_dpp v196, v224, v36 row_newbcast:9 row_mask:0xf bank_mask:0xf
	v_fmac_f32_dpp v197, v225, v37 row_newbcast:9 row_mask:0xf bank_mask:0xf
	v_fmac_f32_dpp v196, v226, v38 row_newbcast:9 row_mask:0xf bank_mask:0xf
	v_fmac_f32_dpp v197, v227, v39 row_newbcast:9 row_mask:0xf bank_mask:0xf
	v_fmac_f32_dpp v196, v224, v40 row_newbcast:10 row_mask:0xf bank_mask:0xf
	v_fmac_f32_dpp v197, v225, v41 row_newbcast:10 row_mask:0xf bank_mask:0xf
	v_fmac_f32_dpp v196, v226, v42 row_newbcast:10 row_mask:0xf bank_mask:0xf
	v_fmac_f32_dpp v197, v227, v43 row_newbcast:10 row_mask:0xf bank_mask:0xf
	v_fmac_f32_dpp v196, v224, v44 row_newbcast:11 row_mask:0xf bank_mask:0xf
	v_fmac_f32_dpp v197, v225, v45 row_newbcast:11 row_mask:0xf bank_mask:0xf
	v_fmac_f32_dpp v196, v226, v46 row_newbcast:11 row_mask:0xf bank_mask:0xf
	v_fmac_f32_dpp v197, v227, v47 row_newbcast:11 row_mask:0xf bank_mask:0xf
	v_fmac_f32_dpp v196, v224, v48 row_newbcast:12 row_mask:0xf bank_mask:0xf
	v_fmac_f32_dpp v197, v225, v49 row_newbcast:12 row_mask:0xf bank_mask:0xf
	v_fmac_f32_dpp v196, v226, v50 row_newbcast:12 row_mask:0xf bank_mask:0xf
	v_fmac_f32_dpp v197, v227, v51 row_newbcast:12 row_mask:0xf bank_mask:0xf
	v_fmac_f32_dpp v196, v224, v52 row_newbcast:13 row_mask:0xf bank_mask:0xf
	v_fmac_f32_dpp v197, v225, v53 row_newbcast:13 row_mask:0xf bank_mask:0xf
	v_fmac_f32_dpp v196, v226, v54 row_newbcast:13 row_mask:0xf bank_mask:0xf
	v_fmac_f32_dpp v197, v227, v55 row_newbcast:13 row_mask:0xf bank_mask:0xf
	v_fmac_f32_dpp v196, v224, v56 row_newbcast:14 row_mask:0xf bank_mask:0xf
	v_fmac_f32_dpp v197, v225, v57 row_newbcast:14 row_mask:0xf bank_mask:0xf
	v_fmac_f32_dpp v196, v226, v58 row_newbcast:14 row_mask:0xf bank_mask:0xf
	v_fmac_f32_dpp v197, v227, v59 row_newbcast:14 row_mask:0xf bank_mask:0xf
	v_fmac_f32_dpp v196, v224, v60 row_newbcast:15 row_mask:0xf bank_mask:0xf
	v_fmac_f32_dpp v197, v225, v61 row_newbcast:15 row_mask:0xf bank_mask:0xf
	v_fmac_f32_dpp v196, v226, v62 row_newbcast:15 row_mask:0xf bank_mask:0xf
	v_fmac_f32_dpp v197, v227, v63 row_newbcast:15 row_mask:0xf bank_mask:0xf
	v_sub_f32_e64 v202, -v196, v197
	s_waitcnt lgkmcnt(0)
	s_nop 1
	v_mfma_f32_4x4x1_16b_f32 v[0:3], v64, v202, v[0:3]
	v_mfma_f32_4x4x1_16b_f32 v[4:7], v65, v202, v[4:7]
	v_mfma_f32_4x4x1_16b_f32 v[8:11], v66, v202, v[8:11]
	v_mfma_f32_4x4x1_16b_f32 v[12:15], v67, v202, v[12:15]
	v_mfma_f32_4x4x1_16b_f32 v[16:19], v68, v202, v[16:19]
	v_mfma_f32_4x4x1_16b_f32 v[20:23], v69, v202, v[20:23]
	v_mfma_f32_4x4x1_16b_f32 v[24:27], v70, v202, v[24:27]
	v_mfma_f32_4x4x1_16b_f32 v[28:31], v71, v202, v[28:31]
	v_mfma_f32_4x4x1_16b_f32 v[32:35], v72, v202, v[32:35]
	v_mfma_f32_4x4x1_16b_f32 v[36:39], v73, v202, v[36:39]
	v_mfma_f32_4x4x1_16b_f32 v[40:43], v74, v202, v[40:43]
	v_mfma_f32_4x4x1_16b_f32 v[44:47], v75, v202, v[44:47]
	v_mfma_f32_4x4x1_16b_f32 v[48:51], v76, v202, v[48:51]
	v_mfma_f32_4x4x1_16b_f32 v[52:55], v77, v202, v[52:55]
	v_mfma_f32_4x4x1_16b_f32 v[56:59], v78, v202, v[56:59]
	v_mfma_f32_4x4x1_16b_f32 v[60:63], v79, v202, v[60:63]
	v_mfma_f32_4x4x1_16b_f32 v[0:3], v80, v114, v[0:3]
	v_mfma_f32_4x4x1_16b_f32 v[4:7], v81, v114, v[4:7]
	v_mfma_f32_4x4x1_16b_f32 v[8:11], v82, v114, v[8:11]
	v_mfma_f32_4x4x1_16b_f32 v[12:15], v83, v114, v[12:15]
	v_mfma_f32_4x4x1_16b_f32 v[16:19], v84, v114, v[16:19]
	v_mfma_f32_4x4x1_16b_f32 v[20:23], v85, v114, v[20:23]
	v_mfma_f32_4x4x1_16b_f32 v[24:27], v86, v114, v[24:27]
	v_mfma_f32_4x4x1_16b_f32 v[28:31], v87, v114, v[28:31]
	v_mfma_f32_4x4x1_16b_f32 v[32:35], v88, v114, v[32:35]
	v_mfma_f32_4x4x1_16b_f32 v[36:39], v89, v114, v[36:39]
	v_mfma_f32_4x4x1_16b_f32 v[40:43], v90, v114, v[40:43]
	v_mfma_f32_4x4x1_16b_f32 v[44:47], v91, v114, v[44:47]
	v_mfma_f32_4x4x1_16b_f32 v[48:51], v92, v114, v[48:51]
	v_mfma_f32_4x4x1_16b_f32 v[52:55], v93, v114, v[52:55]
	v_mfma_f32_4x4x1_16b_f32 v[56:59], v94, v114, v[56:59]
	v_mfma_f32_4x4x1_16b_f32 v[60:63], v95, v114, v[60:63]
	v_fmac_f32_dpp v115, v228, v0 row_newbcast:0 row_mask:0xf bank_mask:0xf
	v_mul_f32_dpp v201, v229, v1 row_newbcast:0 row_mask:0xf bank_mask:0xf
	v_fmac_f32_dpp v115, v230, v2 row_newbcast:0 row_mask:0xf bank_mask:0xf
	v_fmac_f32_dpp v201, v231, v3 row_newbcast:0 row_mask:0xf bank_mask:0xf
	v_fmac_f32_dpp v115, v228, v4 row_newbcast:1 row_mask:0xf bank_mask:0xf
	v_fmac_f32_dpp v201, v229, v5 row_newbcast:1 row_mask:0xf bank_mask:0xf
	v_fmac_f32_dpp v115, v230, v6 row_newbcast:1 row_mask:0xf bank_mask:0xf
	v_fmac_f32_dpp v201, v231, v7 row_newbcast:1 row_mask:0xf bank_mask:0xf
	v_fmac_f32_dpp v115, v228, v8 row_newbcast:2 row_mask:0xf bank_mask:0xf
	v_fmac_f32_dpp v201, v229, v9 row_newbcast:2 row_mask:0xf bank_mask:0xf
	v_fmac_f32_dpp v115, v230, v10 row_newbcast:2 row_mask:0xf bank_mask:0xf
	v_fmac_f32_dpp v201, v231, v11 row_newbcast:2 row_mask:0xf bank_mask:0xf
	v_fmac_f32_dpp v115, v228, v12 row_newbcast:3 row_mask:0xf bank_mask:0xf
	v_fmac_f32_dpp v201, v229, v13 row_newbcast:3 row_mask:0xf bank_mask:0xf
	v_fmac_f32_dpp v115, v230, v14 row_newbcast:3 row_mask:0xf bank_mask:0xf
	v_fmac_f32_dpp v201, v231, v15 row_newbcast:3 row_mask:0xf bank_mask:0xf
	v_fmac_f32_dpp v115, v228, v16 row_newbcast:4 row_mask:0xf bank_mask:0xf
	v_fmac_f32_dpp v201, v229, v17 row_newbcast:4 row_mask:0xf bank_mask:0xf
	v_fmac_f32_dpp v115, v230, v18 row_newbcast:4 row_mask:0xf bank_mask:0xf
	v_fmac_f32_dpp v201, v231, v19 row_newbcast:4 row_mask:0xf bank_mask:0xf
	v_fmac_f32_dpp v115, v228, v20 row_newbcast:5 row_mask:0xf bank_mask:0xf
	v_fmac_f32_dpp v201, v229, v21 row_newbcast:5 row_mask:0xf bank_mask:0xf
	v_fmac_f32_dpp v115, v230, v22 row_newbcast:5 row_mask:0xf bank_mask:0xf
	v_fmac_f32_dpp v201, v231, v23 row_newbcast:5 row_mask:0xf bank_mask:0xf
	v_fmac_f32_dpp v115, v228, v24 row_newbcast:6 row_mask:0xf bank_mask:0xf
	v_fmac_f32_dpp v201, v229, v25 row_newbcast:6 row_mask:0xf bank_mask:0xf
	v_fmac_f32_dpp v115, v230, v26 row_newbcast:6 row_mask:0xf bank_mask:0xf
	v_fmac_f32_dpp v201, v231, v27 row_newbcast:6 row_mask:0xf bank_mask:0xf
	v_fmac_f32_dpp v115, v228, v28 row_newbcast:7 row_mask:0xf bank_mask:0xf
	v_fmac_f32_dpp v201, v229, v29 row_newbcast:7 row_mask:0xf bank_mask:0xf
	v_fmac_f32_dpp v115, v230, v30 row_newbcast:7 row_mask:0xf bank_mask:0xf
	v_fmac_f32_dpp v201, v231, v31 row_newbcast:7 row_mask:0xf bank_mask:0xf
	v_fmac_f32_dpp v115, v228, v32 row_newbcast:8 row_mask:0xf bank_mask:0xf
	v_fmac_f32_dpp v201, v229, v33 row_newbcast:8 row_mask:0xf bank_mask:0xf
	v_fmac_f32_dpp v115, v230, v34 row_newbcast:8 row_mask:0xf bank_mask:0xf
	v_fmac_f32_dpp v201, v231, v35 row_newbcast:8 row_mask:0xf bank_mask:0xf
	v_fmac_f32_dpp v115, v228, v36 row_newbcast:9 row_mask:0xf bank_mask:0xf
	v_fmac_f32_dpp v201, v229, v37 row_newbcast:9 row_mask:0xf bank_mask:0xf
	v_fmac_f32_dpp v115, v230, v38 row_newbcast:9 row_mask:0xf bank_mask:0xf
	v_fmac_f32_dpp v201, v231, v39 row_newbcast:9 row_mask:0xf bank_mask:0xf
	v_fmac_f32_dpp v115, v228, v40 row_newbcast:10 row_mask:0xf bank_mask:0xf
	v_fmac_f32_dpp v201, v229, v41 row_newbcast:10 row_mask:0xf bank_mask:0xf
	v_fmac_f32_dpp v115, v230, v42 row_newbcast:10 row_mask:0xf bank_mask:0xf
	v_fmac_f32_dpp v201, v231, v43 row_newbcast:10 row_mask:0xf bank_mask:0xf
	v_fmac_f32_dpp v115, v228, v44 row_newbcast:11 row_mask:0xf bank_mask:0xf
	v_fmac_f32_dpp v201, v229, v45 row_newbcast:11 row_mask:0xf bank_mask:0xf
	v_fmac_f32_dpp v115, v230, v46 row_newbcast:11 row_mask:0xf bank_mask:0xf
	v_fmac_f32_dpp v201, v231, v47 row_newbcast:11 row_mask:0xf bank_mask:0xf
	v_fmac_f32_dpp v115, v228, v48 row_newbcast:12 row_mask:0xf bank_mask:0xf
	v_fmac_f32_dpp v201, v229, v49 row_newbcast:12 row_mask:0xf bank_mask:0xf
	v_fmac_f32_dpp v115, v230, v50 row_newbcast:12 row_mask:0xf bank_mask:0xf
	v_fmac_f32_dpp v201, v231, v51 row_newbcast:12 row_mask:0xf bank_mask:0xf
	v_fmac_f32_dpp v115, v228, v52 row_newbcast:13 row_mask:0xf bank_mask:0xf
	v_fmac_f32_dpp v201, v229, v53 row_newbcast:13 row_mask:0xf bank_mask:0xf
	v_fmac_f32_dpp v115, v230, v54 row_newbcast:13 row_mask:0xf bank_mask:0xf
	v_fmac_f32_dpp v201, v231, v55 row_newbcast:13 row_mask:0xf bank_mask:0xf
	v_fmac_f32_dpp v115, v228, v56 row_newbcast:14 row_mask:0xf bank_mask:0xf
	v_fmac_f32_dpp v201, v229, v57 row_newbcast:14 row_mask:0xf bank_mask:0xf
	v_fmac_f32_dpp v115, v230, v58 row_newbcast:14 row_mask:0xf bank_mask:0xf
	v_fmac_f32_dpp v201, v231, v59 row_newbcast:14 row_mask:0xf bank_mask:0xf
	v_fmac_f32_dpp v115, v228, v60 row_newbcast:15 row_mask:0xf bank_mask:0xf
	v_fmac_f32_dpp v201, v229, v61 row_newbcast:15 row_mask:0xf bank_mask:0xf
	v_fmac_f32_dpp v115, v230, v62 row_newbcast:15 row_mask:0xf bank_mask:0xf
	v_fmac_f32_dpp v201, v231, v63 row_newbcast:15 row_mask:0xf bank_mask:0xf
	v_add_f32_e32 v200, v115, v201
	s_waitcnt vmcnt(14)
	buffer_store_dword v200, v207, s[68:71], s79 offen
	s_add_u32 s79, s79, 0xfffff000
	buffer_load_dwordx4 v[96:99], v232, s[64:67], s72 offen
	buffer_load_dwordx4 v[100:103], v233, s[64:67], s72 offen
	buffer_load_dwordx4 v[104:107], v234, s[64:67], s72 offen
	buffer_load_dwordx4 v[108:111], v235, s[64:67], s72 offen
	buffer_load_dwordx2 v[112:113], v236, s[64:67], s76 offen
	buffer_load_short_d16_hi v114, v237, s[64:67], s76 offen
	buffer_load_dword v115, v207, s[68:71], s78 offen
	s_add_i32 s72, s72, 0xfffff000
	s_max_i32 s72, s72, 0
	s_add_i32 s76, s76, 0xfffff800
	s_max_i32 s76, s76, 0
	s_add_i32 s78, s78, 0xfffff000
	s_max_i32 s78, s78, 0
	v_pk_mul_f32 v[224:225], v[120:121], v[216:217]
	v_pk_mul_f32 v[226:227], v[122:123], v[218:219]
	v_pk_mul_f32 v[216:217], v[216:217], v[116:117]
	v_pk_mul_f32 v[218:219], v[218:219], v[118:119]
	v_pk_fma_f32 v[184:185], v[124:125], v[188:189], v[192:193]
	v_pk_fma_f32 v[186:187], v[126:127], v[190:191], v[194:195]
	v_pk_mul_f32 v[176:177], v[120:121], v[124:125]
	v_pk_mul_f32 v[178:179], v[122:123], v[126:127]
	v_rcp_f32_e32 v220, v216
	v_rcp_f32_e32 v221, v217
	v_rcp_f32_e32 v222, v218
	v_rcp_f32_e32 v223, v219
	v_lshlrev_b32_e32 v180, 16, v132
	v_and_b32_e32 v181, 0xffff0000, v132
	v_lshlrev_b32_e32 v182, 16, v133
	v_and_b32_e32 v183, 0xffff0000, v133
	v_pk_mul_f32 v[180:181], v[180:181], v[184:185]
	v_pk_mul_f32 v[182:183], v[182:183], v[186:187]
	v_pk_mul_f32 v[228:229], v[128:129], v[216:217]
	v_pk_mul_f32 v[230:231], v[130:131], v[218:219]
	v_pk_mul_f32 v[176:177], v[176:177], v[220:221]
	v_pk_mul_f32 v[178:179], v[178:179], v[222:223]
	v_pk_mul_f32 v[180:181], v[180:181], v[220:221]
	v_pk_mul_f32 v[182:183], v[182:183], v[222:223]
	ds_write2_b32 v208, v176, v177 offset0:0 offset1:16
	ds_write2_b32 v208, v178, v179 offset0:32 offset1:48
	ds_write2_b32 v208, v180, v181 offset0:64 offset1:80
	ds_write2_b32 v208, v182, v183 offset0:96 offset1:112
	ds_read_b128 v[64:67], v209 offset:0
	ds_read_b128 v[68:71], v209 offset:16
	ds_read_b128 v[72:75], v209 offset:32
	ds_read_b128 v[76:79], v209 offset:48
	ds_read_b128 v[80:83], v209 offset:256
	ds_read_b128 v[84:87], v209 offset:272
	ds_read_b128 v[88:91], v209 offset:288
	ds_read_b128 v[92:95], v209 offset:304
	v_mul_f32_dpp v196, v224, v0 row_newbcast:0 row_mask:0xf bank_mask:0xf
	v_mul_f32_dpp v197, v225, v1 row_newbcast:0 row_mask:0xf bank_mask:0xf
	v_fmac_f32_dpp v196, v226, v2 row_newbcast:0 row_mask:0xf bank_mask:0xf
	v_fmac_f32_dpp v197, v227, v3 row_newbcast:0 row_mask:0xf bank_mask:0xf
	v_fmac_f32_dpp v196, v224, v4 row_newbcast:1 row_mask:0xf bank_mask:0xf
	v_fmac_f32_dpp v197, v225, v5 row_newbcast:1 row_mask:0xf bank_mask:0xf
	v_fmac_f32_dpp v196, v226, v6 row_newbcast:1 row_mask:0xf bank_mask:0xf
	v_fmac_f32_dpp v197, v227, v7 row_newbcast:1 row_mask:0xf bank_mask:0xf
	v_fmac_f32_dpp v196, v224, v8 row_newbcast:2 row_mask:0xf bank_mask:0xf
	v_fmac_f32_dpp v197, v225, v9 row_newbcast:2 row_mask:0xf bank_mask:0xf
	v_fmac_f32_dpp v196, v226, v10 row_newbcast:2 row_mask:0xf bank_mask:0xf
	v_fmac_f32_dpp v197, v227, v11 row_newbcast:2 row_mask:0xf bank_mask:0xf
	v_fmac_f32_dpp v196, v224, v12 row_newbcast:3 row_mask:0xf bank_mask:0xf
	v_fmac_f32_dpp v197, v225, v13 row_newbcast:3 row_mask:0xf bank_mask:0xf
	v_fmac_f32_dpp v196, v226, v14 row_newbcast:3 row_mask:0xf bank_mask:0xf
	v_fmac_f32_dpp v197, v227, v15 row_newbcast:3 row_mask:0xf bank_mask:0xf
	v_fmac_f32_dpp v196, v224, v16 row_newbcast:4 row_mask:0xf bank_mask:0xf
	v_fmac_f32_dpp v197, v225, v17 row_newbcast:4 row_mask:0xf bank_mask:0xf
	v_fmac_f32_dpp v196, v226, v18 row_newbcast:4 row_mask:0xf bank_mask:0xf
	v_fmac_f32_dpp v197, v227, v19 row_newbcast:4 row_mask:0xf bank_mask:0xf
	v_fmac_f32_dpp v196, v224, v20 row_newbcast:5 row_mask:0xf bank_mask:0xf
	v_fmac_f32_dpp v197, v225, v21 row_newbcast:5 row_mask:0xf bank_mask:0xf
	v_fmac_f32_dpp v196, v226, v22 row_newbcast:5 row_mask:0xf bank_mask:0xf
	v_fmac_f32_dpp v197, v227, v23 row_newbcast:5 row_mask:0xf bank_mask:0xf
	v_fmac_f32_dpp v196, v224, v24 row_newbcast:6 row_mask:0xf bank_mask:0xf
	v_fmac_f32_dpp v197, v225, v25 row_newbcast:6 row_mask:0xf bank_mask:0xf
	v_fmac_f32_dpp v196, v226, v26 row_newbcast:6 row_mask:0xf bank_mask:0xf
	v_fmac_f32_dpp v197, v227, v27 row_newbcast:6 row_mask:0xf bank_mask:0xf
	v_fmac_f32_dpp v196, v224, v28 row_newbcast:7 row_mask:0xf bank_mask:0xf
	v_fmac_f32_dpp v197, v225, v29 row_newbcast:7 row_mask:0xf bank_mask:0xf
	v_fmac_f32_dpp v196, v226, v30 row_newbcast:7 row_mask:0xf bank_mask:0xf
	v_fmac_f32_dpp v197, v227, v31 row_newbcast:7 row_mask:0xf bank_mask:0xf
	v_fmac_f32_dpp v196, v224, v32 row_newbcast:8 row_mask:0xf bank_mask:0xf
	v_fmac_f32_dpp v197, v225, v33 row_newbcast:8 row_mask:0xf bank_mask:0xf
	v_fmac_f32_dpp v196, v226, v34 row_newbcast:8 row_mask:0xf bank_mask:0xf
	v_fmac_f32_dpp v197, v227, v35 row_newbcast:8 row_mask:0xf bank_mask:0xf
	v_fmac_f32_dpp v196, v224, v36 row_newbcast:9 row_mask:0xf bank_mask:0xf
	v_fmac_f32_dpp v197, v225, v37 row_newbcast:9 row_mask:0xf bank_mask:0xf
	v_fmac_f32_dpp v196, v226, v38 row_newbcast:9 row_mask:0xf bank_mask:0xf
	v_fmac_f32_dpp v197, v227, v39 row_newbcast:9 row_mask:0xf bank_mask:0xf
	v_fmac_f32_dpp v196, v224, v40 row_newbcast:10 row_mask:0xf bank_mask:0xf
	v_fmac_f32_dpp v197, v225, v41 row_newbcast:10 row_mask:0xf bank_mask:0xf
	v_fmac_f32_dpp v196, v226, v42 row_newbcast:10 row_mask:0xf bank_mask:0xf
	v_fmac_f32_dpp v197, v227, v43 row_newbcast:10 row_mask:0xf bank_mask:0xf
	v_fmac_f32_dpp v196, v224, v44 row_newbcast:11 row_mask:0xf bank_mask:0xf
	v_fmac_f32_dpp v197, v225, v45 row_newbcast:11 row_mask:0xf bank_mask:0xf
	v_fmac_f32_dpp v196, v226, v46 row_newbcast:11 row_mask:0xf bank_mask:0xf
	v_fmac_f32_dpp v197, v227, v47 row_newbcast:11 row_mask:0xf bank_mask:0xf
	v_fmac_f32_dpp v196, v224, v48 row_newbcast:12 row_mask:0xf bank_mask:0xf
	v_fmac_f32_dpp v197, v225, v49 row_newbcast:12 row_mask:0xf bank_mask:0xf
	v_fmac_f32_dpp v196, v226, v50 row_newbcast:12 row_mask:0xf bank_mask:0xf
	v_fmac_f32_dpp v197, v227, v51 row_newbcast:12 row_mask:0xf bank_mask:0xf
	v_fmac_f32_dpp v196, v224, v52 row_newbcast:13 row_mask:0xf bank_mask:0xf
	v_fmac_f32_dpp v197, v225, v53 row_newbcast:13 row_mask:0xf bank_mask:0xf
	v_fmac_f32_dpp v196, v226, v54 row_newbcast:13 row_mask:0xf bank_mask:0xf
	v_fmac_f32_dpp v197, v227, v55 row_newbcast:13 row_mask:0xf bank_mask:0xf
	v_fmac_f32_dpp v196, v224, v56 row_newbcast:14 row_mask:0xf bank_mask:0xf
	v_fmac_f32_dpp v197, v225, v57 row_newbcast:14 row_mask:0xf bank_mask:0xf
	v_fmac_f32_dpp v196, v226, v58 row_newbcast:14 row_mask:0xf bank_mask:0xf
	v_fmac_f32_dpp v197, v227, v59 row_newbcast:14 row_mask:0xf bank_mask:0xf
	v_fmac_f32_dpp v196, v224, v60 row_newbcast:15 row_mask:0xf bank_mask:0xf
	v_fmac_f32_dpp v197, v225, v61 row_newbcast:15 row_mask:0xf bank_mask:0xf
	v_fmac_f32_dpp v196, v226, v62 row_newbcast:15 row_mask:0xf bank_mask:0xf
	v_fmac_f32_dpp v197, v227, v63 row_newbcast:15 row_mask:0xf bank_mask:0xf
	v_sub_f32_e64 v202, -v196, v197
	s_waitcnt lgkmcnt(0)
	s_nop 1
	v_mfma_f32_4x4x1_16b_f32 v[0:3], v64, v202, v[0:3]
	v_mfma_f32_4x4x1_16b_f32 v[4:7], v65, v202, v[4:7]
	v_mfma_f32_4x4x1_16b_f32 v[8:11], v66, v202, v[8:11]
	v_mfma_f32_4x4x1_16b_f32 v[12:15], v67, v202, v[12:15]
	v_mfma_f32_4x4x1_16b_f32 v[16:19], v68, v202, v[16:19]
	v_mfma_f32_4x4x1_16b_f32 v[20:23], v69, v202, v[20:23]
	v_mfma_f32_4x4x1_16b_f32 v[24:27], v70, v202, v[24:27]
	v_mfma_f32_4x4x1_16b_f32 v[28:31], v71, v202, v[28:31]
	v_mfma_f32_4x4x1_16b_f32 v[32:35], v72, v202, v[32:35]
	v_mfma_f32_4x4x1_16b_f32 v[36:39], v73, v202, v[36:39]
	v_mfma_f32_4x4x1_16b_f32 v[40:43], v74, v202, v[40:43]
	v_mfma_f32_4x4x1_16b_f32 v[44:47], v75, v202, v[44:47]
	v_mfma_f32_4x4x1_16b_f32 v[48:51], v76, v202, v[48:51]
	v_mfma_f32_4x4x1_16b_f32 v[52:55], v77, v202, v[52:55]
	v_mfma_f32_4x4x1_16b_f32 v[56:59], v78, v202, v[56:59]
	v_mfma_f32_4x4x1_16b_f32 v[60:63], v79, v202, v[60:63]
	v_mfma_f32_4x4x1_16b_f32 v[0:3], v80, v134, v[0:3]
	v_mfma_f32_4x4x1_16b_f32 v[4:7], v81, v134, v[4:7]
	v_mfma_f32_4x4x1_16b_f32 v[8:11], v82, v134, v[8:11]
	v_mfma_f32_4x4x1_16b_f32 v[12:15], v83, v134, v[12:15]
	v_mfma_f32_4x4x1_16b_f32 v[16:19], v84, v134, v[16:19]
	v_mfma_f32_4x4x1_16b_f32 v[20:23], v85, v134, v[20:23]
	v_mfma_f32_4x4x1_16b_f32 v[24:27], v86, v134, v[24:27]
	v_mfma_f32_4x4x1_16b_f32 v[28:31], v87, v134, v[28:31]
	v_mfma_f32_4x4x1_16b_f32 v[32:35], v88, v134, v[32:35]
	v_mfma_f32_4x4x1_16b_f32 v[36:39], v89, v134, v[36:39]
	v_mfma_f32_4x4x1_16b_f32 v[40:43], v90, v134, v[40:43]
	v_mfma_f32_4x4x1_16b_f32 v[44:47], v91, v134, v[44:47]
	v_mfma_f32_4x4x1_16b_f32 v[48:51], v92, v134, v[48:51]
	v_mfma_f32_4x4x1_16b_f32 v[52:55], v93, v134, v[52:55]
	v_mfma_f32_4x4x1_16b_f32 v[56:59], v94, v134, v[56:59]
	v_mfma_f32_4x4x1_16b_f32 v[60:63], v95, v134, v[60:63]
	v_fmac_f32_dpp v135, v228, v0 row_newbcast:0 row_mask:0xf bank_mask:0xf
	v_mul_f32_dpp v201, v229, v1 row_newbcast:0 row_mask:0xf bank_mask:0xf
	v_fmac_f32_dpp v135, v230, v2 row_newbcast:0 row_mask:0xf bank_mask:0xf
	v_fmac_f32_dpp v201, v231, v3 row_newbcast:0 row_mask:0xf bank_mask:0xf
	v_fmac_f32_dpp v135, v228, v4 row_newbcast:1 row_mask:0xf bank_mask:0xf
	v_fmac_f32_dpp v201, v229, v5 row_newbcast:1 row_mask:0xf bank_mask:0xf
	v_fmac_f32_dpp v135, v230, v6 row_newbcast:1 row_mask:0xf bank_mask:0xf
	v_fmac_f32_dpp v201, v231, v7 row_newbcast:1 row_mask:0xf bank_mask:0xf
	v_fmac_f32_dpp v135, v228, v8 row_newbcast:2 row_mask:0xf bank_mask:0xf
	v_fmac_f32_dpp v201, v229, v9 row_newbcast:2 row_mask:0xf bank_mask:0xf
	v_fmac_f32_dpp v135, v230, v10 row_newbcast:2 row_mask:0xf bank_mask:0xf
	v_fmac_f32_dpp v201, v231, v11 row_newbcast:2 row_mask:0xf bank_mask:0xf
	v_fmac_f32_dpp v135, v228, v12 row_newbcast:3 row_mask:0xf bank_mask:0xf
	v_fmac_f32_dpp v201, v229, v13 row_newbcast:3 row_mask:0xf bank_mask:0xf
	v_fmac_f32_dpp v135, v230, v14 row_newbcast:3 row_mask:0xf bank_mask:0xf
	v_fmac_f32_dpp v201, v231, v15 row_newbcast:3 row_mask:0xf bank_mask:0xf
	v_fmac_f32_dpp v135, v228, v16 row_newbcast:4 row_mask:0xf bank_mask:0xf
	v_fmac_f32_dpp v201, v229, v17 row_newbcast:4 row_mask:0xf bank_mask:0xf
	v_fmac_f32_dpp v135, v230, v18 row_newbcast:4 row_mask:0xf bank_mask:0xf
	v_fmac_f32_dpp v201, v231, v19 row_newbcast:4 row_mask:0xf bank_mask:0xf
	v_fmac_f32_dpp v135, v228, v20 row_newbcast:5 row_mask:0xf bank_mask:0xf
	v_fmac_f32_dpp v201, v229, v21 row_newbcast:5 row_mask:0xf bank_mask:0xf
	v_fmac_f32_dpp v135, v230, v22 row_newbcast:5 row_mask:0xf bank_mask:0xf
	v_fmac_f32_dpp v201, v231, v23 row_newbcast:5 row_mask:0xf bank_mask:0xf
	v_fmac_f32_dpp v135, v228, v24 row_newbcast:6 row_mask:0xf bank_mask:0xf
	v_fmac_f32_dpp v201, v229, v25 row_newbcast:6 row_mask:0xf bank_mask:0xf
	v_fmac_f32_dpp v135, v230, v26 row_newbcast:6 row_mask:0xf bank_mask:0xf
	v_fmac_f32_dpp v201, v231, v27 row_newbcast:6 row_mask:0xf bank_mask:0xf
	v_fmac_f32_dpp v135, v228, v28 row_newbcast:7 row_mask:0xf bank_mask:0xf
	v_fmac_f32_dpp v201, v229, v29 row_newbcast:7 row_mask:0xf bank_mask:0xf
	v_fmac_f32_dpp v135, v230, v30 row_newbcast:7 row_mask:0xf bank_mask:0xf
	v_fmac_f32_dpp v201, v231, v31 row_newbcast:7 row_mask:0xf bank_mask:0xf
	v_fmac_f32_dpp v135, v228, v32 row_newbcast:8 row_mask:0xf bank_mask:0xf
	v_fmac_f32_dpp v201, v229, v33 row_newbcast:8 row_mask:0xf bank_mask:0xf
	v_fmac_f32_dpp v135, v230, v34 row_newbcast:8 row_mask:0xf bank_mask:0xf
	v_fmac_f32_dpp v201, v231, v35 row_newbcast:8 row_mask:0xf bank_mask:0xf
	v_fmac_f32_dpp v135, v228, v36 row_newbcast:9 row_mask:0xf bank_mask:0xf
	v_fmac_f32_dpp v201, v229, v37 row_newbcast:9 row_mask:0xf bank_mask:0xf
	v_fmac_f32_dpp v135, v230, v38 row_newbcast:9 row_mask:0xf bank_mask:0xf
	v_fmac_f32_dpp v201, v231, v39 row_newbcast:9 row_mask:0xf bank_mask:0xf
	v_fmac_f32_dpp v135, v228, v40 row_newbcast:10 row_mask:0xf bank_mask:0xf
	v_fmac_f32_dpp v201, v229, v41 row_newbcast:10 row_mask:0xf bank_mask:0xf
	v_fmac_f32_dpp v135, v230, v42 row_newbcast:10 row_mask:0xf bank_mask:0xf
	v_fmac_f32_dpp v201, v231, v43 row_newbcast:10 row_mask:0xf bank_mask:0xf
	v_fmac_f32_dpp v135, v228, v44 row_newbcast:11 row_mask:0xf bank_mask:0xf
	v_fmac_f32_dpp v201, v229, v45 row_newbcast:11 row_mask:0xf bank_mask:0xf
	v_fmac_f32_dpp v135, v230, v46 row_newbcast:11 row_mask:0xf bank_mask:0xf
	v_fmac_f32_dpp v201, v231, v47 row_newbcast:11 row_mask:0xf bank_mask:0xf
	v_fmac_f32_dpp v135, v228, v48 row_newbcast:12 row_mask:0xf bank_mask:0xf
	v_fmac_f32_dpp v201, v229, v49 row_newbcast:12 row_mask:0xf bank_mask:0xf
	v_fmac_f32_dpp v135, v230, v50 row_newbcast:12 row_mask:0xf bank_mask:0xf
	v_fmac_f32_dpp v201, v231, v51 row_newbcast:12 row_mask:0xf bank_mask:0xf
	v_fmac_f32_dpp v135, v228, v52 row_newbcast:13 row_mask:0xf bank_mask:0xf
	v_fmac_f32_dpp v201, v229, v53 row_newbcast:13 row_mask:0xf bank_mask:0xf
	v_fmac_f32_dpp v135, v230, v54 row_newbcast:13 row_mask:0xf bank_mask:0xf
	v_fmac_f32_dpp v201, v231, v55 row_newbcast:13 row_mask:0xf bank_mask:0xf
	v_fmac_f32_dpp v135, v228, v56 row_newbcast:14 row_mask:0xf bank_mask:0xf
	v_fmac_f32_dpp v201, v229, v57 row_newbcast:14 row_mask:0xf bank_mask:0xf
	v_fmac_f32_dpp v135, v230, v58 row_newbcast:14 row_mask:0xf bank_mask:0xf
	v_fmac_f32_dpp v201, v231, v59 row_newbcast:14 row_mask:0xf bank_mask:0xf
	v_fmac_f32_dpp v135, v228, v60 row_newbcast:15 row_mask:0xf bank_mask:0xf
	v_fmac_f32_dpp v201, v229, v61 row_newbcast:15 row_mask:0xf bank_mask:0xf
	v_fmac_f32_dpp v135, v230, v62 row_newbcast:15 row_mask:0xf bank_mask:0xf
	v_fmac_f32_dpp v201, v231, v63 row_newbcast:15 row_mask:0xf bank_mask:0xf
	v_add_f32_e32 v200, v135, v201
	s_waitcnt vmcnt(14)
	buffer_store_dword v200, v207, s[68:71], s79 offen
	s_add_u32 s79, s79, 0xfffff000
	buffer_load_dwordx4 v[116:119], v232, s[64:67], s72 offen
	buffer_load_dwordx4 v[120:123], v233, s[64:67], s72 offen
	buffer_load_dwordx4 v[124:127], v234, s[64:67], s72 offen
	buffer_load_dwordx4 v[128:131], v235, s[64:67], s72 offen
	buffer_load_dwordx2 v[132:133], v236, s[64:67], s76 offen
	buffer_load_short_d16_hi v134, v237, s[64:67], s76 offen
	buffer_load_dword v135, v207, s[68:71], s78 offen
	s_add_i32 s72, s72, 0xfffff000
	s_max_i32 s72, s72, 0
	s_add_i32 s76, s76, 0xfffff800
	s_max_i32 s76, s76, 0
	s_add_i32 s78, s78, 0xfffff000
	s_max_i32 s78, s78, 0
	v_pk_mul_f32 v[224:225], v[140:141], v[216:217]
	v_pk_mul_f32 v[226:227], v[142:143], v[218:219]
	v_pk_mul_f32 v[216:217], v[216:217], v[136:137]
	v_pk_mul_f32 v[218:219], v[218:219], v[138:139]
	v_pk_fma_f32 v[184:185], v[144:145], v[188:189], v[192:193]
	v_pk_fma_f32 v[186:187], v[146:147], v[190:191], v[194:195]
	v_pk_mul_f32 v[176:177], v[140:141], v[144:145]
	v_pk_mul_f32 v[178:179], v[142:143], v[146:147]
	v_rcp_f32_e32 v220, v216
	v_rcp_f32_e32 v221, v217
	v_rcp_f32_e32 v222, v218
	v_rcp_f32_e32 v223, v219
	v_lshlrev_b32_e32 v180, 16, v152
	v_and_b32_e32 v181, 0xffff0000, v152
	v_lshlrev_b32_e32 v182, 16, v153
	v_and_b32_e32 v183, 0xffff0000, v153
	v_pk_mul_f32 v[180:181], v[180:181], v[184:185]
	v_pk_mul_f32 v[182:183], v[182:183], v[186:187]
	v_pk_mul_f32 v[228:229], v[148:149], v[216:217]
	v_pk_mul_f32 v[230:231], v[150:151], v[218:219]
	v_pk_mul_f32 v[176:177], v[176:177], v[220:221]
	v_pk_mul_f32 v[178:179], v[178:179], v[222:223]
	v_pk_mul_f32 v[180:181], v[180:181], v[220:221]
	v_pk_mul_f32 v[182:183], v[182:183], v[222:223]
	ds_write2_b32 v208, v176, v177 offset0:0 offset1:16
	ds_write2_b32 v208, v178, v179 offset0:32 offset1:48
	ds_write2_b32 v208, v180, v181 offset0:64 offset1:80
	ds_write2_b32 v208, v182, v183 offset0:96 offset1:112
	ds_read_b128 v[64:67], v209 offset:0
	ds_read_b128 v[68:71], v209 offset:16
	ds_read_b128 v[72:75], v209 offset:32
	ds_read_b128 v[76:79], v209 offset:48
	ds_read_b128 v[80:83], v209 offset:256
	ds_read_b128 v[84:87], v209 offset:272
	ds_read_b128 v[88:91], v209 offset:288
	ds_read_b128 v[92:95], v209 offset:304
	v_mul_f32_dpp v196, v224, v0 row_newbcast:0 row_mask:0xf bank_mask:0xf
	v_mul_f32_dpp v197, v225, v1 row_newbcast:0 row_mask:0xf bank_mask:0xf
	v_fmac_f32_dpp v196, v226, v2 row_newbcast:0 row_mask:0xf bank_mask:0xf
	v_fmac_f32_dpp v197, v227, v3 row_newbcast:0 row_mask:0xf bank_mask:0xf
	v_fmac_f32_dpp v196, v224, v4 row_newbcast:1 row_mask:0xf bank_mask:0xf
	v_fmac_f32_dpp v197, v225, v5 row_newbcast:1 row_mask:0xf bank_mask:0xf
	v_fmac_f32_dpp v196, v226, v6 row_newbcast:1 row_mask:0xf bank_mask:0xf
	v_fmac_f32_dpp v197, v227, v7 row_newbcast:1 row_mask:0xf bank_mask:0xf
	v_fmac_f32_dpp v196, v224, v8 row_newbcast:2 row_mask:0xf bank_mask:0xf
	v_fmac_f32_dpp v197, v225, v9 row_newbcast:2 row_mask:0xf bank_mask:0xf
	v_fmac_f32_dpp v196, v226, v10 row_newbcast:2 row_mask:0xf bank_mask:0xf
	v_fmac_f32_dpp v197, v227, v11 row_newbcast:2 row_mask:0xf bank_mask:0xf
	v_fmac_f32_dpp v196, v224, v12 row_newbcast:3 row_mask:0xf bank_mask:0xf
	v_fmac_f32_dpp v197, v225, v13 row_newbcast:3 row_mask:0xf bank_mask:0xf
	v_fmac_f32_dpp v196, v226, v14 row_newbcast:3 row_mask:0xf bank_mask:0xf
	v_fmac_f32_dpp v197, v227, v15 row_newbcast:3 row_mask:0xf bank_mask:0xf
	v_fmac_f32_dpp v196, v224, v16 row_newbcast:4 row_mask:0xf bank_mask:0xf
	v_fmac_f32_dpp v197, v225, v17 row_newbcast:4 row_mask:0xf bank_mask:0xf
	v_fmac_f32_dpp v196, v226, v18 row_newbcast:4 row_mask:0xf bank_mask:0xf
	v_fmac_f32_dpp v197, v227, v19 row_newbcast:4 row_mask:0xf bank_mask:0xf
	v_fmac_f32_dpp v196, v224, v20 row_newbcast:5 row_mask:0xf bank_mask:0xf
	v_fmac_f32_dpp v197, v225, v21 row_newbcast:5 row_mask:0xf bank_mask:0xf
	v_fmac_f32_dpp v196, v226, v22 row_newbcast:5 row_mask:0xf bank_mask:0xf
	v_fmac_f32_dpp v197, v227, v23 row_newbcast:5 row_mask:0xf bank_mask:0xf
	v_fmac_f32_dpp v196, v224, v24 row_newbcast:6 row_mask:0xf bank_mask:0xf
	v_fmac_f32_dpp v197, v225, v25 row_newbcast:6 row_mask:0xf bank_mask:0xf
	v_fmac_f32_dpp v196, v226, v26 row_newbcast:6 row_mask:0xf bank_mask:0xf
	v_fmac_f32_dpp v197, v227, v27 row_newbcast:6 row_mask:0xf bank_mask:0xf
	v_fmac_f32_dpp v196, v224, v28 row_newbcast:7 row_mask:0xf bank_mask:0xf
	v_fmac_f32_dpp v197, v225, v29 row_newbcast:7 row_mask:0xf bank_mask:0xf
	v_fmac_f32_dpp v196, v226, v30 row_newbcast:7 row_mask:0xf bank_mask:0xf
	v_fmac_f32_dpp v197, v227, v31 row_newbcast:7 row_mask:0xf bank_mask:0xf
	v_fmac_f32_dpp v196, v224, v32 row_newbcast:8 row_mask:0xf bank_mask:0xf
	v_fmac_f32_dpp v197, v225, v33 row_newbcast:8 row_mask:0xf bank_mask:0xf
	v_fmac_f32_dpp v196, v226, v34 row_newbcast:8 row_mask:0xf bank_mask:0xf
	v_fmac_f32_dpp v197, v227, v35 row_newbcast:8 row_mask:0xf bank_mask:0xf
	v_fmac_f32_dpp v196, v224, v36 row_newbcast:9 row_mask:0xf bank_mask:0xf
	v_fmac_f32_dpp v197, v225, v37 row_newbcast:9 row_mask:0xf bank_mask:0xf
	v_fmac_f32_dpp v196, v226, v38 row_newbcast:9 row_mask:0xf bank_mask:0xf
	v_fmac_f32_dpp v197, v227, v39 row_newbcast:9 row_mask:0xf bank_mask:0xf
	v_fmac_f32_dpp v196, v224, v40 row_newbcast:10 row_mask:0xf bank_mask:0xf
	v_fmac_f32_dpp v197, v225, v41 row_newbcast:10 row_mask:0xf bank_mask:0xf
	v_fmac_f32_dpp v196, v226, v42 row_newbcast:10 row_mask:0xf bank_mask:0xf
	v_fmac_f32_dpp v197, v227, v43 row_newbcast:10 row_mask:0xf bank_mask:0xf
	v_fmac_f32_dpp v196, v224, v44 row_newbcast:11 row_mask:0xf bank_mask:0xf
	v_fmac_f32_dpp v197, v225, v45 row_newbcast:11 row_mask:0xf bank_mask:0xf
	v_fmac_f32_dpp v196, v226, v46 row_newbcast:11 row_mask:0xf bank_mask:0xf
	v_fmac_f32_dpp v197, v227, v47 row_newbcast:11 row_mask:0xf bank_mask:0xf
	v_fmac_f32_dpp v196, v224, v48 row_newbcast:12 row_mask:0xf bank_mask:0xf
	v_fmac_f32_dpp v197, v225, v49 row_newbcast:12 row_mask:0xf bank_mask:0xf
	v_fmac_f32_dpp v196, v226, v50 row_newbcast:12 row_mask:0xf bank_mask:0xf
	v_fmac_f32_dpp v197, v227, v51 row_newbcast:12 row_mask:0xf bank_mask:0xf
	v_fmac_f32_dpp v196, v224, v52 row_newbcast:13 row_mask:0xf bank_mask:0xf
	v_fmac_f32_dpp v197, v225, v53 row_newbcast:13 row_mask:0xf bank_mask:0xf
	v_fmac_f32_dpp v196, v226, v54 row_newbcast:13 row_mask:0xf bank_mask:0xf
	v_fmac_f32_dpp v197, v227, v55 row_newbcast:13 row_mask:0xf bank_mask:0xf
	v_fmac_f32_dpp v196, v224, v56 row_newbcast:14 row_mask:0xf bank_mask:0xf
	v_fmac_f32_dpp v197, v225, v57 row_newbcast:14 row_mask:0xf bank_mask:0xf
	v_fmac_f32_dpp v196, v226, v58 row_newbcast:14 row_mask:0xf bank_mask:0xf
	v_fmac_f32_dpp v197, v227, v59 row_newbcast:14 row_mask:0xf bank_mask:0xf
	v_fmac_f32_dpp v196, v224, v60 row_newbcast:15 row_mask:0xf bank_mask:0xf
	v_fmac_f32_dpp v197, v225, v61 row_newbcast:15 row_mask:0xf bank_mask:0xf
	v_fmac_f32_dpp v196, v226, v62 row_newbcast:15 row_mask:0xf bank_mask:0xf
	v_fmac_f32_dpp v197, v227, v63 row_newbcast:15 row_mask:0xf bank_mask:0xf
	v_sub_f32_e64 v202, -v196, v197
	s_waitcnt lgkmcnt(0)
	s_nop 1
	v_mfma_f32_4x4x1_16b_f32 v[0:3], v64, v202, v[0:3]
	v_mfma_f32_4x4x1_16b_f32 v[4:7], v65, v202, v[4:7]
	v_mfma_f32_4x4x1_16b_f32 v[8:11], v66, v202, v[8:11]
	v_mfma_f32_4x4x1_16b_f32 v[12:15], v67, v202, v[12:15]
	v_mfma_f32_4x4x1_16b_f32 v[16:19], v68, v202, v[16:19]
	v_mfma_f32_4x4x1_16b_f32 v[20:23], v69, v202, v[20:23]
	v_mfma_f32_4x4x1_16b_f32 v[24:27], v70, v202, v[24:27]
	v_mfma_f32_4x4x1_16b_f32 v[28:31], v71, v202, v[28:31]
	v_mfma_f32_4x4x1_16b_f32 v[32:35], v72, v202, v[32:35]
	v_mfma_f32_4x4x1_16b_f32 v[36:39], v73, v202, v[36:39]
	v_mfma_f32_4x4x1_16b_f32 v[40:43], v74, v202, v[40:43]
	v_mfma_f32_4x4x1_16b_f32 v[44:47], v75, v202, v[44:47]
	v_mfma_f32_4x4x1_16b_f32 v[48:51], v76, v202, v[48:51]
	v_mfma_f32_4x4x1_16b_f32 v[52:55], v77, v202, v[52:55]
	v_mfma_f32_4x4x1_16b_f32 v[56:59], v78, v202, v[56:59]
	v_mfma_f32_4x4x1_16b_f32 v[60:63], v79, v202, v[60:63]
	v_mfma_f32_4x4x1_16b_f32 v[0:3], v80, v154, v[0:3]
	v_mfma_f32_4x4x1_16b_f32 v[4:7], v81, v154, v[4:7]
	v_mfma_f32_4x4x1_16b_f32 v[8:11], v82, v154, v[8:11]
	v_mfma_f32_4x4x1_16b_f32 v[12:15], v83, v154, v[12:15]
	v_mfma_f32_4x4x1_16b_f32 v[16:19], v84, v154, v[16:19]
	v_mfma_f32_4x4x1_16b_f32 v[20:23], v85, v154, v[20:23]
	v_mfma_f32_4x4x1_16b_f32 v[24:27], v86, v154, v[24:27]
	v_mfma_f32_4x4x1_16b_f32 v[28:31], v87, v154, v[28:31]
	v_mfma_f32_4x4x1_16b_f32 v[32:35], v88, v154, v[32:35]
	v_mfma_f32_4x4x1_16b_f32 v[36:39], v89, v154, v[36:39]
	v_mfma_f32_4x4x1_16b_f32 v[40:43], v90, v154, v[40:43]
	v_mfma_f32_4x4x1_16b_f32 v[44:47], v91, v154, v[44:47]
	v_mfma_f32_4x4x1_16b_f32 v[48:51], v92, v154, v[48:51]
	v_mfma_f32_4x4x1_16b_f32 v[52:55], v93, v154, v[52:55]
	v_mfma_f32_4x4x1_16b_f32 v[56:59], v94, v154, v[56:59]
	v_mfma_f32_4x4x1_16b_f32 v[60:63], v95, v154, v[60:63]
	v_fmac_f32_dpp v155, v228, v0 row_newbcast:0 row_mask:0xf bank_mask:0xf
	v_mul_f32_dpp v201, v229, v1 row_newbcast:0 row_mask:0xf bank_mask:0xf
	v_fmac_f32_dpp v155, v230, v2 row_newbcast:0 row_mask:0xf bank_mask:0xf
	v_fmac_f32_dpp v201, v231, v3 row_newbcast:0 row_mask:0xf bank_mask:0xf
	v_fmac_f32_dpp v155, v228, v4 row_newbcast:1 row_mask:0xf bank_mask:0xf
	v_fmac_f32_dpp v201, v229, v5 row_newbcast:1 row_mask:0xf bank_mask:0xf
	v_fmac_f32_dpp v155, v230, v6 row_newbcast:1 row_mask:0xf bank_mask:0xf
	v_fmac_f32_dpp v201, v231, v7 row_newbcast:1 row_mask:0xf bank_mask:0xf
	v_fmac_f32_dpp v155, v228, v8 row_newbcast:2 row_mask:0xf bank_mask:0xf
	v_fmac_f32_dpp v201, v229, v9 row_newbcast:2 row_mask:0xf bank_mask:0xf
	v_fmac_f32_dpp v155, v230, v10 row_newbcast:2 row_mask:0xf bank_mask:0xf
	v_fmac_f32_dpp v201, v231, v11 row_newbcast:2 row_mask:0xf bank_mask:0xf
	v_fmac_f32_dpp v155, v228, v12 row_newbcast:3 row_mask:0xf bank_mask:0xf
	v_fmac_f32_dpp v201, v229, v13 row_newbcast:3 row_mask:0xf bank_mask:0xf
	v_fmac_f32_dpp v155, v230, v14 row_newbcast:3 row_mask:0xf bank_mask:0xf
	v_fmac_f32_dpp v201, v231, v15 row_newbcast:3 row_mask:0xf bank_mask:0xf
	v_fmac_f32_dpp v155, v228, v16 row_newbcast:4 row_mask:0xf bank_mask:0xf
	v_fmac_f32_dpp v201, v229, v17 row_newbcast:4 row_mask:0xf bank_mask:0xf
	v_fmac_f32_dpp v155, v230, v18 row_newbcast:4 row_mask:0xf bank_mask:0xf
	v_fmac_f32_dpp v201, v231, v19 row_newbcast:4 row_mask:0xf bank_mask:0xf
	v_fmac_f32_dpp v155, v228, v20 row_newbcast:5 row_mask:0xf bank_mask:0xf
	v_fmac_f32_dpp v201, v229, v21 row_newbcast:5 row_mask:0xf bank_mask:0xf
	v_fmac_f32_dpp v155, v230, v22 row_newbcast:5 row_mask:0xf bank_mask:0xf
	v_fmac_f32_dpp v201, v231, v23 row_newbcast:5 row_mask:0xf bank_mask:0xf
	v_fmac_f32_dpp v155, v228, v24 row_newbcast:6 row_mask:0xf bank_mask:0xf
	v_fmac_f32_dpp v201, v229, v25 row_newbcast:6 row_mask:0xf bank_mask:0xf
	v_fmac_f32_dpp v155, v230, v26 row_newbcast:6 row_mask:0xf bank_mask:0xf
	v_fmac_f32_dpp v201, v231, v27 row_newbcast:6 row_mask:0xf bank_mask:0xf
	v_fmac_f32_dpp v155, v228, v28 row_newbcast:7 row_mask:0xf bank_mask:0xf
	v_fmac_f32_dpp v201, v229, v29 row_newbcast:7 row_mask:0xf bank_mask:0xf
	v_fmac_f32_dpp v155, v230, v30 row_newbcast:7 row_mask:0xf bank_mask:0xf
	v_fmac_f32_dpp v201, v231, v31 row_newbcast:7 row_mask:0xf bank_mask:0xf
	v_fmac_f32_dpp v155, v228, v32 row_newbcast:8 row_mask:0xf bank_mask:0xf
	v_fmac_f32_dpp v201, v229, v33 row_newbcast:8 row_mask:0xf bank_mask:0xf
	v_fmac_f32_dpp v155, v230, v34 row_newbcast:8 row_mask:0xf bank_mask:0xf
	v_fmac_f32_dpp v201, v231, v35 row_newbcast:8 row_mask:0xf bank_mask:0xf
	v_fmac_f32_dpp v155, v228, v36 row_newbcast:9 row_mask:0xf bank_mask:0xf
	v_fmac_f32_dpp v201, v229, v37 row_newbcast:9 row_mask:0xf bank_mask:0xf
	v_fmac_f32_dpp v155, v230, v38 row_newbcast:9 row_mask:0xf bank_mask:0xf
	v_fmac_f32_dpp v201, v231, v39 row_newbcast:9 row_mask:0xf bank_mask:0xf
	v_fmac_f32_dpp v155, v228, v40 row_newbcast:10 row_mask:0xf bank_mask:0xf
	v_fmac_f32_dpp v201, v229, v41 row_newbcast:10 row_mask:0xf bank_mask:0xf
	v_fmac_f32_dpp v155, v230, v42 row_newbcast:10 row_mask:0xf bank_mask:0xf
	v_fmac_f32_dpp v201, v231, v43 row_newbcast:10 row_mask:0xf bank_mask:0xf
	v_fmac_f32_dpp v155, v228, v44 row_newbcast:11 row_mask:0xf bank_mask:0xf
	v_fmac_f32_dpp v201, v229, v45 row_newbcast:11 row_mask:0xf bank_mask:0xf
	v_fmac_f32_dpp v155, v230, v46 row_newbcast:11 row_mask:0xf bank_mask:0xf
	v_fmac_f32_dpp v201, v231, v47 row_newbcast:11 row_mask:0xf bank_mask:0xf
	v_fmac_f32_dpp v155, v228, v48 row_newbcast:12 row_mask:0xf bank_mask:0xf
	v_fmac_f32_dpp v201, v229, v49 row_newbcast:12 row_mask:0xf bank_mask:0xf
	v_fmac_f32_dpp v155, v230, v50 row_newbcast:12 row_mask:0xf bank_mask:0xf
	v_fmac_f32_dpp v201, v231, v51 row_newbcast:12 row_mask:0xf bank_mask:0xf
	v_fmac_f32_dpp v155, v228, v52 row_newbcast:13 row_mask:0xf bank_mask:0xf
	v_fmac_f32_dpp v201, v229, v53 row_newbcast:13 row_mask:0xf bank_mask:0xf
	v_fmac_f32_dpp v155, v230, v54 row_newbcast:13 row_mask:0xf bank_mask:0xf
	v_fmac_f32_dpp v201, v231, v55 row_newbcast:13 row_mask:0xf bank_mask:0xf
	v_fmac_f32_dpp v155, v228, v56 row_newbcast:14 row_mask:0xf bank_mask:0xf
	v_fmac_f32_dpp v201, v229, v57 row_newbcast:14 row_mask:0xf bank_mask:0xf
	v_fmac_f32_dpp v155, v230, v58 row_newbcast:14 row_mask:0xf bank_mask:0xf
	v_fmac_f32_dpp v201, v231, v59 row_newbcast:14 row_mask:0xf bank_mask:0xf
	v_fmac_f32_dpp v155, v228, v60 row_newbcast:15 row_mask:0xf bank_mask:0xf
	v_fmac_f32_dpp v201, v229, v61 row_newbcast:15 row_mask:0xf bank_mask:0xf
	v_fmac_f32_dpp v155, v230, v62 row_newbcast:15 row_mask:0xf bank_mask:0xf
	v_fmac_f32_dpp v201, v231, v63 row_newbcast:15 row_mask:0xf bank_mask:0xf
	v_add_f32_e32 v200, v155, v201
	s_waitcnt vmcnt(14)
	buffer_store_dword v200, v207, s[68:71], s79 offen
	s_add_u32 s79, s79, 0xfffff000
	buffer_load_dwordx4 v[136:139], v232, s[64:67], s72 offen
	buffer_load_dwordx4 v[140:143], v233, s[64:67], s72 offen
	buffer_load_dwordx4 v[144:147], v234, s[64:67], s72 offen
	buffer_load_dwordx4 v[148:151], v235, s[64:67], s72 offen
	buffer_load_dwordx2 v[152:153], v236, s[64:67], s76 offen
	buffer_load_short_d16_hi v154, v237, s[64:67], s76 offen
	buffer_load_dword v155, v207, s[68:71], s78 offen
	s_add_i32 s72, s72, 0xfffff000
	s_max_i32 s72, s72, 0
	s_add_i32 s76, s76, 0xfffff800
	s_max_i32 s76, s76, 0
	s_add_i32 s78, s78, 0xfffff000
	s_max_i32 s78, s78, 0
	v_pk_mul_f32 v[224:225], v[160:161], v[216:217]
	v_pk_mul_f32 v[226:227], v[162:163], v[218:219]
	v_pk_mul_f32 v[216:217], v[216:217], v[156:157]
	v_pk_mul_f32 v[218:219], v[218:219], v[158:159]
	v_pk_fma_f32 v[184:185], v[164:165], v[188:189], v[192:193]
	v_pk_fma_f32 v[186:187], v[166:167], v[190:191], v[194:195]
	v_pk_mul_f32 v[176:177], v[160:161], v[164:165]
	v_pk_mul_f32 v[178:179], v[162:163], v[166:167]
	v_rcp_f32_e32 v220, v216
	v_rcp_f32_e32 v221, v217
	v_rcp_f32_e32 v222, v218
	v_rcp_f32_e32 v223, v219
	v_lshlrev_b32_e32 v180, 16, v172
	v_and_b32_e32 v181, 0xffff0000, v172
	v_lshlrev_b32_e32 v182, 16, v173
	v_and_b32_e32 v183, 0xffff0000, v173
	v_pk_mul_f32 v[180:181], v[180:181], v[184:185]
	v_pk_mul_f32 v[182:183], v[182:183], v[186:187]
	v_pk_mul_f32 v[228:229], v[168:169], v[216:217]
	v_pk_mul_f32 v[230:231], v[170:171], v[218:219]
	v_pk_mul_f32 v[176:177], v[176:177], v[220:221]
	v_pk_mul_f32 v[178:179], v[178:179], v[222:223]
	v_pk_mul_f32 v[180:181], v[180:181], v[220:221]
	v_pk_mul_f32 v[182:183], v[182:183], v[222:223]
	ds_write2_b32 v208, v176, v177 offset0:0 offset1:16
	ds_write2_b32 v208, v178, v179 offset0:32 offset1:48
	ds_write2_b32 v208, v180, v181 offset0:64 offset1:80
	ds_write2_b32 v208, v182, v183 offset0:96 offset1:112
	ds_read_b128 v[64:67], v209 offset:0
	ds_read_b128 v[68:71], v209 offset:16
	ds_read_b128 v[72:75], v209 offset:32
	ds_read_b128 v[76:79], v209 offset:48
	ds_read_b128 v[80:83], v209 offset:256
	ds_read_b128 v[84:87], v209 offset:272
	ds_read_b128 v[88:91], v209 offset:288
	ds_read_b128 v[92:95], v209 offset:304
	v_mul_f32_dpp v196, v224, v0 row_newbcast:0 row_mask:0xf bank_mask:0xf
	v_mul_f32_dpp v197, v225, v1 row_newbcast:0 row_mask:0xf bank_mask:0xf
	v_fmac_f32_dpp v196, v226, v2 row_newbcast:0 row_mask:0xf bank_mask:0xf
	v_fmac_f32_dpp v197, v227, v3 row_newbcast:0 row_mask:0xf bank_mask:0xf
	v_fmac_f32_dpp v196, v224, v4 row_newbcast:1 row_mask:0xf bank_mask:0xf
	v_fmac_f32_dpp v197, v225, v5 row_newbcast:1 row_mask:0xf bank_mask:0xf
	v_fmac_f32_dpp v196, v226, v6 row_newbcast:1 row_mask:0xf bank_mask:0xf
	v_fmac_f32_dpp v197, v227, v7 row_newbcast:1 row_mask:0xf bank_mask:0xf
	v_fmac_f32_dpp v196, v224, v8 row_newbcast:2 row_mask:0xf bank_mask:0xf
	v_fmac_f32_dpp v197, v225, v9 row_newbcast:2 row_mask:0xf bank_mask:0xf
	v_fmac_f32_dpp v196, v226, v10 row_newbcast:2 row_mask:0xf bank_mask:0xf
	v_fmac_f32_dpp v197, v227, v11 row_newbcast:2 row_mask:0xf bank_mask:0xf
	v_fmac_f32_dpp v196, v224, v12 row_newbcast:3 row_mask:0xf bank_mask:0xf
	v_fmac_f32_dpp v197, v225, v13 row_newbcast:3 row_mask:0xf bank_mask:0xf
	v_fmac_f32_dpp v196, v226, v14 row_newbcast:3 row_mask:0xf bank_mask:0xf
	v_fmac_f32_dpp v197, v227, v15 row_newbcast:3 row_mask:0xf bank_mask:0xf
	v_fmac_f32_dpp v196, v224, v16 row_newbcast:4 row_mask:0xf bank_mask:0xf
	v_fmac_f32_dpp v197, v225, v17 row_newbcast:4 row_mask:0xf bank_mask:0xf
	v_fmac_f32_dpp v196, v226, v18 row_newbcast:4 row_mask:0xf bank_mask:0xf
	v_fmac_f32_dpp v197, v227, v19 row_newbcast:4 row_mask:0xf bank_mask:0xf
	v_fmac_f32_dpp v196, v224, v20 row_newbcast:5 row_mask:0xf bank_mask:0xf
	v_fmac_f32_dpp v197, v225, v21 row_newbcast:5 row_mask:0xf bank_mask:0xf
	v_fmac_f32_dpp v196, v226, v22 row_newbcast:5 row_mask:0xf bank_mask:0xf
	v_fmac_f32_dpp v197, v227, v23 row_newbcast:5 row_mask:0xf bank_mask:0xf
	v_fmac_f32_dpp v196, v224, v24 row_newbcast:6 row_mask:0xf bank_mask:0xf
	v_fmac_f32_dpp v197, v225, v25 row_newbcast:6 row_mask:0xf bank_mask:0xf
	v_fmac_f32_dpp v196, v226, v26 row_newbcast:6 row_mask:0xf bank_mask:0xf
	v_fmac_f32_dpp v197, v227, v27 row_newbcast:6 row_mask:0xf bank_mask:0xf
	v_fmac_f32_dpp v196, v224, v28 row_newbcast:7 row_mask:0xf bank_mask:0xf
	v_fmac_f32_dpp v197, v225, v29 row_newbcast:7 row_mask:0xf bank_mask:0xf
	v_fmac_f32_dpp v196, v226, v30 row_newbcast:7 row_mask:0xf bank_mask:0xf
	v_fmac_f32_dpp v197, v227, v31 row_newbcast:7 row_mask:0xf bank_mask:0xf
	v_fmac_f32_dpp v196, v224, v32 row_newbcast:8 row_mask:0xf bank_mask:0xf
	v_fmac_f32_dpp v197, v225, v33 row_newbcast:8 row_mask:0xf bank_mask:0xf
	v_fmac_f32_dpp v196, v226, v34 row_newbcast:8 row_mask:0xf bank_mask:0xf
	v_fmac_f32_dpp v197, v227, v35 row_newbcast:8 row_mask:0xf bank_mask:0xf
	v_fmac_f32_dpp v196, v224, v36 row_newbcast:9 row_mask:0xf bank_mask:0xf
	v_fmac_f32_dpp v197, v225, v37 row_newbcast:9 row_mask:0xf bank_mask:0xf
	v_fmac_f32_dpp v196, v226, v38 row_newbcast:9 row_mask:0xf bank_mask:0xf
	v_fmac_f32_dpp v197, v227, v39 row_newbcast:9 row_mask:0xf bank_mask:0xf
	v_fmac_f32_dpp v196, v224, v40 row_newbcast:10 row_mask:0xf bank_mask:0xf
	v_fmac_f32_dpp v197, v225, v41 row_newbcast:10 row_mask:0xf bank_mask:0xf
	v_fmac_f32_dpp v196, v226, v42 row_newbcast:10 row_mask:0xf bank_mask:0xf
	v_fmac_f32_dpp v197, v227, v43 row_newbcast:10 row_mask:0xf bank_mask:0xf
	v_fmac_f32_dpp v196, v224, v44 row_newbcast:11 row_mask:0xf bank_mask:0xf
	v_fmac_f32_dpp v197, v225, v45 row_newbcast:11 row_mask:0xf bank_mask:0xf
	v_fmac_f32_dpp v196, v226, v46 row_newbcast:11 row_mask:0xf bank_mask:0xf
	v_fmac_f32_dpp v197, v227, v47 row_newbcast:11 row_mask:0xf bank_mask:0xf
	v_fmac_f32_dpp v196, v224, v48 row_newbcast:12 row_mask:0xf bank_mask:0xf
	v_fmac_f32_dpp v197, v225, v49 row_newbcast:12 row_mask:0xf bank_mask:0xf
	v_fmac_f32_dpp v196, v226, v50 row_newbcast:12 row_mask:0xf bank_mask:0xf
	v_fmac_f32_dpp v197, v227, v51 row_newbcast:12 row_mask:0xf bank_mask:0xf
	v_fmac_f32_dpp v196, v224, v52 row_newbcast:13 row_mask:0xf bank_mask:0xf
	v_fmac_f32_dpp v197, v225, v53 row_newbcast:13 row_mask:0xf bank_mask:0xf
	v_fmac_f32_dpp v196, v226, v54 row_newbcast:13 row_mask:0xf bank_mask:0xf
	v_fmac_f32_dpp v197, v227, v55 row_newbcast:13 row_mask:0xf bank_mask:0xf
	v_fmac_f32_dpp v196, v224, v56 row_newbcast:14 row_mask:0xf bank_mask:0xf
	v_fmac_f32_dpp v197, v225, v57 row_newbcast:14 row_mask:0xf bank_mask:0xf
	v_fmac_f32_dpp v196, v226, v58 row_newbcast:14 row_mask:0xf bank_mask:0xf
	v_fmac_f32_dpp v197, v227, v59 row_newbcast:14 row_mask:0xf bank_mask:0xf
	v_fmac_f32_dpp v196, v224, v60 row_newbcast:15 row_mask:0xf bank_mask:0xf
	v_fmac_f32_dpp v197, v225, v61 row_newbcast:15 row_mask:0xf bank_mask:0xf
	v_fmac_f32_dpp v196, v226, v62 row_newbcast:15 row_mask:0xf bank_mask:0xf
	v_fmac_f32_dpp v197, v227, v63 row_newbcast:15 row_mask:0xf bank_mask:0xf
	v_sub_f32_e64 v202, -v196, v197
	s_waitcnt lgkmcnt(0)
; #define SB __builtin_amdgcn_sched_barrier(0)
; #define ST2(set, s) { DERIVE_BK(set); float sd[4]; ScanK<0>::dot(S, set.a, sd); float y0 = set.yo, y1 = 0.f; ScanK<0>::upd(S, set, -((sd[0] + sd[1]) + (sd[2] + sd[3])), __uint_as_float(set.v << 16), y0, y1); __builtin_amdgcn_raw_buffer_store_b32(__float_as_uint(y0 + y1), rY, lo4b, ob4 + (unsigned)((int)(s) * (int)stp * 4), 0); }
;     static __device__ __forceinline__ void upd(float (&S)[64], const In2& in, float sa, float vv, float& y0, float& y1) {
;         float t0, t1, t2, t3;
;         asm volatile("v_mul_f32_dpp %0, %10, %27 row_newbcast:%28" DPPM "v_mul_f32_dpp %1, %11, %27 row_newbcast:%28" DPPM "v_mul_f32_dpp %2, %12, %27 row_newbcast:%28" DPPM "v_mul_f32_dpp %3, %13, %27 row_newbcast:%28" DPPM
;                      "v_fmac_f32_dpp %0, %14, %6 row_newbcast:%28" DPPM "v_fmac_f32_dpp %1, %15, %7 row_newbcast:%28" DPPM "v_fmac_f32_dpp %2, %16, %8 row_newbcast:%28" DPPM "v_fmac_f32_dpp %3, %17, %9 row_newbcast:%28" DPPM
;                      "v_fmac_f32_dpp %0, %18, %26 row_newbcast:%28" DPPM "v_fmac_f32_dpp %1, %19, %26 row_newbcast:%28" DPPM "v_fmac_f32_dpp %2, %20, %26 row_newbcast:%28" DPPM "v_fmac_f32_dpp %3, %21, %26 row_newbcast:%28" DPPM
;                      "v_fmac_f32_dpp %4, %22, %0 row_newbcast:%28" DPPM "v_fmac_f32_dpp %5, %23, %1 row_newbcast:%28" DPPM "v_fmac_f32_dpp %4, %24, %2 row_newbcast:%28" DPPM "v_fmac_f32_dpp %5, %25, %3 row_newbcast:%28" DPPM
;                      : "=&v"(t0), "=&v"(t1), "=&v"(t2), "=&v"(t3), "+v"(y0), "+v"(y1)
;                      : "v"(S[K]), "v"(S[K + 1]), "v"(S[K + 2]), "v"(S[K + 3]), "v"(in.kd[0]), "v"(in.kd[1]), "v"(in.kd[2]), "v"(in.kd[3]), "v"(in.w[0]), "v"(in.w[1]), "v"(in.w[2]), "v"(in.w[3]),
;                        "v"(in.b[0]), "v"(in.b[1]), "v"(in.b[2]), "v"(in.b[3]), "v"(in.r[0]), "v"(in.r[1]), "v"(in.r[2]), "v"(in.r[3]), "v"(sa), "v"(vv), "n"(N0));
;         S[K] = t0; S[K + 1] = t1; S[K + 2] = t2; S[K + 3] = t3;
;         if constexpr (K + 4 < 64) ScanK<K + 4>::upd(S, in, sa, vv, y0, y1);
;     }
; __device__ __forceinline__ void scan_pass2(const Params& p, int d) {
;     ...
;         In2 i0, i1; LD2(i0, 0);
; #pragma unroll 1
;         for (int s = 0; s < LC; s += 2) { TOUCH2(i0); SB; LD2(i1, s + 1); SB; ST2(i0, s); TOUCH2(i1); SB; LD2(i0, s + 2); SB; ST2(i1, s + 1); }
	s_nop 1
	v_mfma_f32_4x4x1_16b_f32 v[0:3], v64, v202, v[0:3]
	v_mfma_f32_4x4x1_16b_f32 v[4:7], v65, v202, v[4:7]
	v_mfma_f32_4x4x1_16b_f32 v[8:11], v66, v202, v[8:11]
	v_mfma_f32_4x4x1_16b_f32 v[12:15], v67, v202, v[12:15]
	v_mfma_f32_4x4x1_16b_f32 v[16:19], v68, v202, v[16:19]
	v_mfma_f32_4x4x1_16b_f32 v[20:23], v69, v202, v[20:23]
	v_mfma_f32_4x4x1_16b_f32 v[24:27], v70, v202, v[24:27]
	v_mfma_f32_4x4x1_16b_f32 v[28:31], v71, v202, v[28:31]
	v_mfma_f32_4x4x1_16b_f32 v[32:35], v72, v202, v[32:35]
	v_mfma_f32_4x4x1_16b_f32 v[36:39], v73, v202, v[36:39]
	v_mfma_f32_4x4x1_16b_f32 v[40:43], v74, v202, v[40:43]
	v_mfma_f32_4x4x1_16b_f32 v[44:47], v75, v202, v[44:47]
	v_mfma_f32_4x4x1_16b_f32 v[48:51], v76, v202, v[48:51]
	v_mfma_f32_4x4x1_16b_f32 v[52:55], v77, v202, v[52:55]
	v_mfma_f32_4x4x1_16b_f32 v[56:59], v78, v202, v[56:59]
	v_mfma_f32_4x4x1_16b_f32 v[60:63], v79, v202, v[60:63]
	v_mfma_f32_4x4x1_16b_f32 v[0:3], v80, v174, v[0:3]
	v_mfma_f32_4x4x1_16b_f32 v[4:7], v81, v174, v[4:7]
	v_mfma_f32_4x4x1_16b_f32 v[8:11], v82, v174, v[8:11]
	v_mfma_f32_4x4x1_16b_f32 v[12:15], v83, v174, v[12:15]
	v_mfma_f32_4x4x1_16b_f32 v[16:19], v84, v174, v[16:19]
	v_mfma_f32_4x4x1_16b_f32 v[20:23], v85, v174, v[20:23]
	v_mfma_f32_4x4x1_16b_f32 v[24:27], v86, v174, v[24:27]
	v_mfma_f32_4x4x1_16b_f32 v[28:31], v87, v174, v[28:31]
	v_mfma_f32_4x4x1_16b_f32 v[32:35], v88, v174, v[32:35]
	v_mfma_f32_4x4x1_16b_f32 v[36:39], v89, v174, v[36:39]
	v_mfma_f32_4x4x1_16b_f32 v[40:43], v90, v174, v[40:43]
	v_mfma_f32_4x4x1_16b_f32 v[44:47], v91, v174, v[44:47]
	v_mfma_f32_4x4x1_16b_f32 v[48:51], v92, v174, v[48:51]
	v_mfma_f32_4x4x1_16b_f32 v[52:55], v93, v174, v[52:55]
	v_mfma_f32_4x4x1_16b_f32 v[56:59], v94, v174, v[56:59]
	v_mfma_f32_4x4x1_16b_f32 v[60:63], v95, v174, v[60:63]
	v_fmac_f32_dpp v175, v228, v0 row_newbcast:0 row_mask:0xf bank_mask:0xf
	v_mul_f32_dpp v201, v229, v1 row_newbcast:0 row_mask:0xf bank_mask:0xf
	v_fmac_f32_dpp v175, v230, v2 row_newbcast:0 row_mask:0xf bank_mask:0xf
	v_fmac_f32_dpp v201, v231, v3 row_newbcast:0 row_mask:0xf bank_mask:0xf
	v_fmac_f32_dpp v175, v228, v4 row_newbcast:1 row_mask:0xf bank_mask:0xf
	v_fmac_f32_dpp v201, v229, v5 row_newbcast:1 row_mask:0xf bank_mask:0xf
	v_fmac_f32_dpp v175, v230, v6 row_newbcast:1 row_mask:0xf bank_mask:0xf
	v_fmac_f32_dpp v201, v231, v7 row_newbcast:1 row_mask:0xf bank_mask:0xf
	v_fmac_f32_dpp v175, v228, v8 row_newbcast:2 row_mask:0xf bank_mask:0xf
	v_fmac_f32_dpp v201, v229, v9 row_newbcast:2 row_mask:0xf bank_mask:0xf
	v_fmac_f32_dpp v175, v230, v10 row_newbcast:2 row_mask:0xf bank_mask:0xf
	v_fmac_f32_dpp v201, v231, v11 row_newbcast:2 row_mask:0xf bank_mask:0xf
	v_fmac_f32_dpp v175, v228, v12 row_newbcast:3 row_mask:0xf bank_mask:0xf
	v_fmac_f32_dpp v201, v229, v13 row_newbcast:3 row_mask:0xf bank_mask:0xf
	v_fmac_f32_dpp v175, v230, v14 row_newbcast:3 row_mask:0xf bank_mask:0xf
	v_fmac_f32_dpp v201, v231, v15 row_newbcast:3 row_mask:0xf bank_mask:0xf
	v_fmac_f32_dpp v175, v228, v16 row_newbcast:4 row_mask:0xf bank_mask:0xf
	v_fmac_f32_dpp v201, v229, v17 row_newbcast:4 row_mask:0xf bank_mask:0xf
	v_fmac_f32_dpp v175, v230, v18 row_newbcast:4 row_mask:0xf bank_mask:0xf
	v_fmac_f32_dpp v201, v231, v19 row_newbcast:4 row_mask:0xf bank_mask:0xf
	v_fmac_f32_dpp v175, v228, v20 row_newbcast:5 row_mask:0xf bank_mask:0xf
	v_fmac_f32_dpp v201, v229, v21 row_newbcast:5 row_mask:0xf bank_mask:0xf
	v_fmac_f32_dpp v175, v230, v22 row_newbcast:5 row_mask:0xf bank_mask:0xf
	v_fmac_f32_dpp v201, v231, v23 row_newbcast:5 row_mask:0xf bank_mask:0xf
	v_fmac_f32_dpp v175, v228, v24 row_newbcast:6 row_mask:0xf bank_mask:0xf
	v_fmac_f32_dpp v201, v229, v25 row_newbcast:6 row_mask:0xf bank_mask:0xf
	v_fmac_f32_dpp v175, v230, v26 row_newbcast:6 row_mask:0xf bank_mask:0xf
	v_fmac_f32_dpp v201, v231, v27 row_newbcast:6 row_mask:0xf bank_mask:0xf
	v_fmac_f32_dpp v175, v228, v28 row_newbcast:7 row_mask:0xf bank_mask:0xf
	v_fmac_f32_dpp v201, v229, v29 row_newbcast:7 row_mask:0xf bank_mask:0xf
	v_fmac_f32_dpp v175, v230, v30 row_newbcast:7 row_mask:0xf bank_mask:0xf
	v_fmac_f32_dpp v201, v231, v31 row_newbcast:7 row_mask:0xf bank_mask:0xf
	v_fmac_f32_dpp v175, v228, v32 row_newbcast:8 row_mask:0xf bank_mask:0xf
	v_fmac_f32_dpp v201, v229, v33 row_newbcast:8 row_mask:0xf bank_mask:0xf
	v_fmac_f32_dpp v175, v230, v34 row_newbcast:8 row_mask:0xf bank_mask:0xf
	v_fmac_f32_dpp v201, v231, v35 row_newbcast:8 row_mask:0xf bank_mask:0xf
	v_fmac_f32_dpp v175, v228, v36 row_newbcast:9 row_mask:0xf bank_mask:0xf
	v_fmac_f32_dpp v201, v229, v37 row_newbcast:9 row_mask:0xf bank_mask:0xf
	v_fmac_f32_dpp v175, v230, v38 row_newbcast:9 row_mask:0xf bank_mask:0xf
	v_fmac_f32_dpp v201, v231, v39 row_newbcast:9 row_mask:0xf bank_mask:0xf
	v_fmac_f32_dpp v175, v228, v40 row_newbcast:10 row_mask:0xf bank_mask:0xf
	v_fmac_f32_dpp v201, v229, v41 row_newbcast:10 row_mask:0xf bank_mask:0xf
	v_fmac_f32_dpp v175, v230, v42 row_newbcast:10 row_mask:0xf bank_mask:0xf
	v_fmac_f32_dpp v201, v231, v43 row_newbcast:10 row_mask:0xf bank_mask:0xf
	v_fmac_f32_dpp v175, v228, v44 row_newbcast:11 row_mask:0xf bank_mask:0xf
	v_fmac_f32_dpp v201, v229, v45 row_newbcast:11 row_mask:0xf bank_mask:0xf
	v_fmac_f32_dpp v175, v230, v46 row_newbcast:11 row_mask:0xf bank_mask:0xf
	v_fmac_f32_dpp v201, v231, v47 row_newbcast:11 row_mask:0xf bank_mask:0xf
	v_fmac_f32_dpp v175, v228, v48 row_newbcast:12 row_mask:0xf bank_mask:0xf
	v_fmac_f32_dpp v201, v229, v49 row_newbcast:12 row_mask:0xf bank_mask:0xf
	v_fmac_f32_dpp v175, v230, v50 row_newbcast:12 row_mask:0xf bank_mask:0xf
	v_fmac_f32_dpp v201, v231, v51 row_newbcast:12 row_mask:0xf bank_mask:0xf
	v_fmac_f32_dpp v175, v228, v52 row_newbcast:13 row_mask:0xf bank_mask:0xf
	v_fmac_f32_dpp v201, v229, v53 row_newbcast:13 row_mask:0xf bank_mask:0xf
	v_fmac_f32_dpp v175, v230, v54 row_newbcast:13 row_mask:0xf bank_mask:0xf
	v_fmac_f32_dpp v201, v231, v55 row_newbcast:13 row_mask:0xf bank_mask:0xf
	v_fmac_f32_dpp v175, v228, v56 row_newbcast:14 row_mask:0xf bank_mask:0xf
	v_fmac_f32_dpp v201, v229, v57 row_newbcast:14 row_mask:0xf bank_mask:0xf
	v_fmac_f32_dpp v175, v230, v58 row_newbcast:14 row_mask:0xf bank_mask:0xf
	v_fmac_f32_dpp v201, v231, v59 row_newbcast:14 row_mask:0xf bank_mask:0xf
	v_fmac_f32_dpp v175, v228, v60 row_newbcast:15 row_mask:0xf bank_mask:0xf
	v_fmac_f32_dpp v201, v229, v61 row_newbcast:15 row_mask:0xf bank_mask:0xf
	v_fmac_f32_dpp v175, v230, v62 row_newbcast:15 row_mask:0xf bank_mask:0xf
	v_fmac_f32_dpp v201, v231, v63 row_newbcast:15 row_mask:0xf bank_mask:0xf
	v_add_f32_e32 v200, v175, v201
	s_sub_u32 s83, s83, 1
	s_cmp_eq_u32 s83, 0
	s_cbranch_scc1 .Lmy_p2d1_ldone
	s_and_b32 s9, s83, 7
	s_cmp_eq_u32 s9, 0
	s_cbranch_scc1 .Lmy_p2d1_renorm
	s_branch .Lmy_p2d1_loop
